# P5 fused epilogue de-serialised (x loads for all row groups in flight, gain hoisted, stores without per-store waits) + attention epilogue loads hoisted
# speedup vs baseline: 1.3226x; 1.3226x over previous
; __device__ __forceinline__ unsigned pk2(float lo, float hi) { f32x2_t v = {lo, hi}; bf16x2_t b = __builtin_convertvector(v, bf16x2_t); return __builtin_bit_cast(unsigned, b); }
; __device__ __forceinline__ float bflo(unsigned v) { return __uint_as_float(v << 16); }
; __device__ __forceinline__ float bfhi(unsigned v) { return __uint_as_float(v & 0xffff0000u); }
; __device__ void attn_item(const Params& p, char* lds, int bh, int qi) {
;     ...
;   lsum += __shfl_xor(lsum, 32);
;   const float inv = __builtin_amdgcn_rcpf(lsum);
;   const int b = bh >> 3, hd = bh & 7;
;   const size_t tok = (size_t)b * SEQ + qpos;
;   const u16* ga = p.GA + tok * 512 + hd * 64;
;   u16* yo = p.Ymix + tok * 1024 + hd * 64;
; #pragma unroll
;   for (int d = 0; d < 2; ++d)
; #pragma unroll
;     for (int rq = 0; rq < 4; ++rq) {
;       const int c = d * 32 + 8 * rq + 4 * h;
;       const u32x2 g = *(const u32x2*)(ga + c);
;       u32x2 w;
;       w.x = pk2(O[d][rq * 4 + 0] * inv * bflo(g.x), O[d][rq * 4 + 1] * inv * bfhi(g.x));
;       w.y = pk2(O[d][rq * 4 + 2] * inv * bflo(g.y), O[d][rq * 4 + 3] * inv * bfhi(g.y));
;       *(u32x2*)(yo + c) = w;
;     }
.LBB0_392:
	v_lshl_add_u32 v94, s36, 9, v94
	v_lshlrev_b64 v[34:35], 10, v[94:95]
	v_lshl_add_u64 v[34:35], v[98:99], 0, v[34:35]
	global_load_dwordx2 v[44:45], v[34:35], off
	global_load_dwordx2 v[46:47], v[34:35], off offset:16
	global_load_dwordx2 v[48:49], v[34:35], off offset:32
	global_load_dwordx2 v[50:51], v[34:35], off offset:48
	global_load_dwordx2 v[52:53], v[34:35], off offset:64
	global_load_dwordx2 v[54:55], v[34:35], off offset:80
	global_load_dwordx2 v[56:57], v[34:35], off offset:96
	global_load_dwordx2 v[58:59], v[34:35], off offset:112
	v_cmp_lt_i32_e32 vcc, v156, v157
	v_lshlrev_b64 v[40:41], 11, v[94:95]
	v_lshl_add_u64 v[40:41], v[100:101], 0, v[40:41]
	v_cndmask_b32_e32 v38, v1, v156, vcc
	v_lshlrev_b32_e32 v38, 2, v38
	ds_bpermute_b32 v38, v38, v126
	s_mov_b64 s[4:5], 0
	s_waitcnt lgkmcnt(0)
	v_add_f32_e32 v38, v126, v38
	v_rcp_f32_e32 v38, v38
	s_nop 0
	s_waitcnt vmcnt(7)
	v_lshlrev_b32_e32 v42, 16, v44
	v_and_b32_e32 v43, 0xffff0000, v44
	v_lshlrev_b32_e32 v36, 16, v45
	v_and_b32_e32 v37, 0xffff0000, v45
	v_pk_mul_f32 v[18:19], v[18:19], v[38:39] op_sel_hi:[1,0]
	v_pk_mul_f32 v[20:21], v[20:21], v[38:39] op_sel_hi:[1,0]
	v_pk_mul_f32 v[18:19], v[18:19], v[42:43]
	v_pk_mul_f32 v[20:21], v[20:21], v[36:37]
	v_cvt_pk_bf16_f32 v60, v18, v19
	v_cvt_pk_bf16_f32 v61, v20, v21
	global_store_dwordx2 v[40:41], v[60:61], off
	s_waitcnt vmcnt(7)
	v_lshlrev_b32_e32 v42, 16, v46
	v_and_b32_e32 v43, 0xffff0000, v46
	v_lshlrev_b32_e32 v36, 16, v47
	v_and_b32_e32 v37, 0xffff0000, v47
	v_pk_mul_f32 v[22:23], v[22:23], v[38:39] op_sel_hi:[1,0]
	v_pk_mul_f32 v[24:25], v[24:25], v[38:39] op_sel_hi:[1,0]
	v_pk_mul_f32 v[22:23], v[22:23], v[42:43]
	v_pk_mul_f32 v[24:25], v[24:25], v[36:37]
	v_cvt_pk_bf16_f32 v62, v22, v23
	v_cvt_pk_bf16_f32 v63, v24, v25
	global_store_dwordx2 v[40:41], v[62:63], off offset:16
	s_waitcnt vmcnt(7)
	v_lshlrev_b32_e32 v42, 16, v48
	v_and_b32_e32 v43, 0xffff0000, v48
	v_lshlrev_b32_e32 v36, 16, v49
	v_and_b32_e32 v37, 0xffff0000, v49
	v_pk_mul_f32 v[26:27], v[26:27], v[38:39] op_sel_hi:[1,0]
	v_pk_mul_f32 v[28:29], v[28:29], v[38:39] op_sel_hi:[1,0]
	v_pk_mul_f32 v[26:27], v[26:27], v[42:43]
	v_pk_mul_f32 v[28:29], v[28:29], v[36:37]
	v_cvt_pk_bf16_f32 v64, v26, v27
	v_cvt_pk_bf16_f32 v65, v28, v29
	global_store_dwordx2 v[40:41], v[64:65], off offset:32
	s_waitcnt vmcnt(7)
	v_lshlrev_b32_e32 v42, 16, v50
	v_and_b32_e32 v43, 0xffff0000, v50
	v_lshlrev_b32_e32 v36, 16, v51
	v_and_b32_e32 v37, 0xffff0000, v51
	v_pk_mul_f32 v[30:31], v[30:31], v[38:39] op_sel_hi:[1,0]
	v_pk_mul_f32 v[32:33], v[32:33], v[38:39] op_sel_hi:[1,0]
	v_pk_mul_f32 v[30:31], v[30:31], v[42:43]
	v_pk_mul_f32 v[32:33], v[32:33], v[36:37]
	v_cvt_pk_bf16_f32 v66, v30, v31
	v_cvt_pk_bf16_f32 v67, v32, v33
	global_store_dwordx2 v[40:41], v[66:67], off offset:48
	s_waitcnt vmcnt(7)
	v_lshlrev_b32_e32 v42, 16, v52
	v_and_b32_e32 v43, 0xffff0000, v52
	v_lshlrev_b32_e32 v36, 16, v53
	v_and_b32_e32 v37, 0xffff0000, v53
	v_pk_mul_f32 v[2:3], v[2:3], v[38:39] op_sel_hi:[1,0]
	v_pk_mul_f32 v[4:5], v[4:5], v[38:39] op_sel_hi:[1,0]
	v_pk_mul_f32 v[2:3], v[2:3], v[42:43]
	v_pk_mul_f32 v[4:5], v[4:5], v[36:37]
	v_cvt_pk_bf16_f32 v68, v2, v3
	v_cvt_pk_bf16_f32 v69, v4, v5
	global_store_dwordx2 v[40:41], v[68:69], off offset:64
	s_waitcnt vmcnt(7)
	v_lshlrev_b32_e32 v42, 16, v54
	v_and_b32_e32 v43, 0xffff0000, v54
	v_lshlrev_b32_e32 v36, 16, v55
	v_and_b32_e32 v37, 0xffff0000, v55
	v_pk_mul_f32 v[6:7], v[6:7], v[38:39] op_sel_hi:[1,0]
	v_pk_mul_f32 v[8:9], v[8:9], v[38:39] op_sel_hi:[1,0]
	v_pk_mul_f32 v[6:7], v[6:7], v[42:43]
	v_pk_mul_f32 v[8:9], v[8:9], v[36:37]
	v_cvt_pk_bf16_f32 v70, v6, v7
	v_cvt_pk_bf16_f32 v71, v8, v9
	global_store_dwordx2 v[40:41], v[70:71], off offset:80
	s_waitcnt vmcnt(7)
	v_lshlrev_b32_e32 v42, 16, v56
	v_and_b32_e32 v43, 0xffff0000, v56
	v_lshlrev_b32_e32 v36, 16, v57
	v_and_b32_e32 v37, 0xffff0000, v57
	v_pk_mul_f32 v[10:11], v[10:11], v[38:39] op_sel_hi:[1,0]
	v_pk_mul_f32 v[12:13], v[12:13], v[38:39] op_sel_hi:[1,0]
	v_pk_mul_f32 v[10:11], v[10:11], v[42:43]
	v_pk_mul_f32 v[12:13], v[12:13], v[36:37]
	v_cvt_pk_bf16_f32 v72, v10, v11
	v_cvt_pk_bf16_f32 v73, v12, v13
	global_store_dwordx2 v[40:41], v[72:73], off offset:96
	s_waitcnt vmcnt(7)
	v_lshlrev_b32_e32 v42, 16, v58
	v_and_b32_e32 v43, 0xffff0000, v58
	v_lshlrev_b32_e32 v36, 16, v59
	v_and_b32_e32 v37, 0xffff0000, v59
	v_pk_mul_f32 v[14:15], v[14:15], v[38:39] op_sel_hi:[1,0]
	v_pk_mul_f32 v[16:17], v[16:17], v[38:39] op_sel_hi:[1,0]
	v_pk_mul_f32 v[14:15], v[14:15], v[42:43]
	v_pk_mul_f32 v[16:17], v[16:17], v[36:37]
	v_cvt_pk_bf16_f32 v74, v14, v15
	v_cvt_pk_bf16_f32 v75, v16, v17
	global_store_dwordx2 v[40:41], v[74:75], off offset:112

;     ...
;   const int srow = tid >> 3, skc = tid & 7;
;   const u16* Ag = A + (size_t)(m0 + srow) * K + skc * 8;
;   const u16* Bg[4];
; #pragma unroll
;   for (int i = 0; i < 4; ++i) { int n = n0 + srow + 64 * i; n = n < nmax ? n : nmax - 1; Bg[i] = Bt + (size_t)n * K + skc * 8; }
;   const int nk = nk_override ? nk_override : K / 64;
; #pragma unroll
;   for (int i = 0; i < 4; ++i) { ra[i] = *(const u32x4*)(Ag + (size_t)(64 * i) * K); rb[i] = *(const u32x4*)(Bg[i]); }
; #pragma unroll
;   for (int i = 0; i < 4; ++i) { *(u32x4*)(As0 + (srow + 64 * i) * LD + skc * 8) = ra[i]; *(u32x4*)(Bs0 + (srow + 64 * i) * LD + skc * 8) = rb[i]; }
;   if (nk > 1) {
; #pragma unroll
;     for (int i = 0; i < 4; ++i) { ra[i] = *(const u32x4*)(Ag + (size_t)(64 * i) * K + 64); rb[i] = *(const u32x4*)(Bg[i] + 64); }
;   }
;   for (int kt = 0; kt < nk; ++kt) {
;     __syncthreads();
;     if (kt + 1 < nk) {
;       u16* aw = As0 + ((kt + 1) & 1) * 256 * LD;
;       u16* bw = Bs0 + ((kt + 1) & 1) * 256 * LD;
; #pragma unroll
;       for (int i = 0; i < 4; ++i) { *(u32x4*)(aw + (srow + 64 * i) * LD + skc * 8) = ra[i]; *(u32x4*)(bw + (srow + 64 * i) * LD + skc * 8) = rb[i]; }
;     }
;     if (kt + 2 < nk) {
; #pragma unroll
;       for (int i = 0; i < 4; ++i) { ra[i] = *(const u32x4*)(Ag + (size_t)(64 * i) * K + (kt + 2) * 64); rb[i] = *(const u32x4*)(Bg[i] + (kt + 2) * 64); }
;     }
;     __builtin_amdgcn_sched_barrier(0);
;     const u16* as = As0 + (kt & 1) * 256 * LD + (wr * 128 + l31) * LD + h * 8;
;     const u16* bs = Bs0 + (kt & 1) * 256 * LD + (wc * 64 + l31) * LD + h * 8;
;     if (domma)
; #pragma unroll
;     for (int ks = 0; ks < 4; ++ks) {
;       bf16x8 wf[2], xf[4];
; #pragma unroll
;       for (int ct = 0; ct < 2; ++ct) wf[ct] = *(const bf16x8*)(bs + ct * 32 * LD + ks * 16);
; #pragma unroll
;       for (int tt = 0; tt < 4; ++tt) xf[tt] = *(const bf16x8*)(as + tt * 32 * LD + ks * 16);
; #pragma unroll
;       for (int ct = 0; ct < 2; ++ct)
; #pragma unroll
;         for (int tt = 0; tt < 4; ++tt) acc[ct][tt] = __builtin_amdgcn_mfma_f32_32x32x16_bf16(wf[ct], xf[tt], acc[ct][tt], 0, 0, 0);
; __device__ void phase_gemm2(const Params& p, char* lds, int bid, int nb, bool fused) {
;     ...
;   const int xcd = bid & 7, jx = bid >> 3, nbx = (nb + 7 - xcd) >> 3;
;   for (int Lx = jx; Lx < (NMT / 8) * NNT; Lx += nbx) {
;     const int mt = xcd * (NMT / 8) + Lx / NNT, nt = Lx % NNT;
.LBB0_554:
	s_ashr_i32 s4, s3, 31
	s_lshr_b32 s4, s4, 30
	s_add_i32 s4, s3, s4
	s_and_b32 s5, s4, 0xfffffc
	s_sub_i32 s5, s3, s5
	v_mov_b32_e32 v66, v223
	s_lshl_b32 s34, s5, 8
	s_lshl_b32 s4, s4, 6
	v_ashrrev_i32_e32 v40, 3, v66
	v_add_u32_e32 v8, s34, v40
	s_and_b32 s38, s4, 0xffffff00
	v_lshlrev_b32_e32 v4, 4, v66
	v_min_i32_e32 v6, 0x3ff, v8
	s_add_i32 s38, s38, s44
	v_and_b32_e32 v150, 0x70, v4
	v_ashrrev_i32_e32 v7, 31, v6
	v_add_u32_e32 v2, s38, v40
	s_waitcnt lgkmcnt(0)
	v_lshl_add_u64 v[4:5], s[22:23], 0, v[150:151]
	v_lshlrev_b64 v[6:7], 11, v[6:7]
	v_ashrrev_i32_e32 v3, 31, v2
	v_lshl_add_u64 v[130:131], v[4:5], 0, v[6:7]
	v_min_i32_e32 v6, 0x3bf, v8
	v_lshlrev_b64 v[2:3], 11, v[2:3]
	v_ashrrev_i32_e32 v7, 31, v6
	v_lshlrev_b64 v[6:7], 11, v[6:7]
	v_lshl_add_u64 v[2:3], s[16:17], 0, v[2:3]
	v_lshl_add_u64 v[34:35], v[4:5], 0, v[6:7]
	v_min_i32_e32 v6, 0x37f, v8
	v_lshl_add_u64 v[132:133], v[2:3], 0, v[150:151]
	v_ashrrev_i32_e32 v7, 31, v6
	v_add_co_u32_e32 v134, vcc, s45, v132
	v_lshlrev_b64 v[6:7], 11, v[6:7]
	s_nop 0
	v_addc_co_u32_e32 v135, vcc, 0, v133, vcc
	v_lshl_add_u64 v[36:37], v[4:5], 0, v[6:7]
	v_min_i32_e32 v6, 0x33f, v8
	v_add_co_u32_e32 v14, vcc, s45, v34
	v_ashrrev_i32_e32 v7, 31, v6
	s_nop 0
	v_addc_co_u32_e32 v15, vcc, 0, v35, vcc
	v_lshlrev_b64 v[6:7], 11, v[6:7]
	v_add_co_u32_e32 v136, vcc, s46, v132
	v_lshl_add_u64 v[38:39], v[4:5], 0, v[6:7]
	global_load_dwordx4 v[2:5], v[132:133], off
	global_load_dwordx4 v[6:9], v[130:131], off
	v_addc_co_u32_e32 v137, vcc, 0, v133, vcc
	v_add_co_u32_e32 v22, vcc, s46, v36
	global_load_dwordx4 v[10:13], v[134:135], off
	global_load_dwordx4 v[18:21], v[136:137], off
	v_addc_co_u32_e32 v23, vcc, 0, v37, vcc
	global_load_dwordx4 v[14:17], v[14:15], off
	v_add_co_u32_e32 v138, vcc, s47, v132
	global_load_dwordx4 v[22:25], v[22:23], off
	s_nop 0
	v_addc_co_u32_e32 v139, vcc, 0, v133, vcc
	v_add_co_u32_e32 v30, vcc, s47, v38
	global_load_dwordx4 v[26:29], v[138:139], off
	s_nop 0
	v_addc_co_u32_e32 v31, vcc, 0, v39, vcc
	global_load_dwordx4 v[30:33], v[30:31], off
	v_mul_lo_u32 v40, v40, s52
	v_add3_u32 v149, 0, v150, v40
	v_lshl_add_u64 v[144:145], v[38:39], 0, s[30:31]
	v_add3_u32 v152, s51, v150, v40
	v_lshl_add_u64 v[140:141], v[34:35], 0, s[26:27]
	v_lshl_add_u64 v[142:143], v[36:37], 0, s[28:29]
	global_load_dwordx4 v[34:37], v[132:133], off offset:128
	global_load_dwordx4 v[38:41], v[130:131], off offset:128
	global_load_dwordx4 v[42:45], v[134:135], off offset:128
	global_load_dwordx4 v[46:49], v[136:137], off offset:128
	global_load_dwordx4 v[50:53], v[140:141], off offset:128
	global_load_dwordx4 v[54:57], v[142:143], off offset:128
	global_load_dwordx4 v[58:61], v[138:139], off offset:128
	global_load_dwordx4 v[62:65], v[144:145], off offset:128
	v_readfirstlane_b32 s5, v66
	s_and_b32 s4, s5, 0xc0
	s_ashr_i32 s5, s5, 1
	v_and_b32_e32 v146, 31, v66
	s_and_b32 s5, s5, 0xffffff80
	v_bfe_u32 v159, v66, 5, 1
	v_lshlrev_b32_e32 v150, 4, v159
	s_waitcnt vmcnt(15)
	ds_write_b128 v149, v[2:5]
	s_waitcnt vmcnt(14)
	ds_write_b128 v152, v[6:9]
	s_waitcnt vmcnt(13)
	ds_write_b128 v149, v[10:13] offset:9216
	s_waitcnt vmcnt(11)
	ds_write_b128 v152, v[14:17] offset:9216
	ds_write_b128 v149, v[18:21] offset:18432
	s_waitcnt vmcnt(10)
	ds_write_b128 v152, v[22:25] offset:18432
	s_waitcnt vmcnt(9)
	ds_write_b128 v149, v[26:29] offset:27648
	s_waitcnt vmcnt(8)
	ds_write_b128 v152, v[30:33] offset:27648
	s_waitcnt lgkmcnt(0)
	s_barrier
	global_load_dwordx4 v[160:163], v[144:145], off offset:256
	global_load_dwordx4 v[164:167], v[142:143], off offset:256
	global_load_dwordx4 v[168:171], v[138:139], off offset:256
	global_load_dwordx4 v[172:175], v[136:137], off offset:256
	global_load_dwordx4 v[176:179], v[140:141], off offset:256
	global_load_dwordx4 v[180:183], v[130:131], off offset:256
	global_load_dwordx4 v[184:187], v[134:135], off offset:256
	global_load_dwordx4 v[188:191], v[132:133], off offset:256
	v_or_b32_e32 v2, s5, v146
	v_mul_lo_u32 v2, v2, s52
	v_add3_u32 v147, 0, v2, v150
	v_or_b32_e32 v2, s4, v146
	v_mul_u32_u24_e32 v2, 0x90, v2
	v_add3_u32 v148, s51, v2, v150
	s_waitcnt vmcnt(15)
	ds_write_b128 v149, v[34:37] offset:36864
	s_waitcnt vmcnt(14)
	ds_write_b128 v152, v[38:41] offset:36864
	s_waitcnt vmcnt(13)
	ds_write_b128 v149, v[42:45] offset:46080
	s_waitcnt vmcnt(11)
	ds_write_b128 v152, v[50:53] offset:46080
	ds_write_b128 v149, v[46:49] offset:55296
	s_waitcnt vmcnt(10)
	ds_write_b128 v152, v[54:57] offset:55296
	s_waitcnt vmcnt(9)
	ds_write_b128 v149, v[58:61] offset:64512
	s_waitcnt vmcnt(8)
	ds_write_b128 v152, v[62:65] offset:64512
	ds_read_b128 v[2:5], v148
	ds_read_b128 v[6:9], v147
	ds_read_b128 v[192:195], v148 offset:32
	ds_read_b128 v[196:199], v147 offset:32
	ds_read_b128 v[10:13], v147 offset:4608
	ds_read_b128 v[200:203], v147 offset:4640
	ds_read_b128 v[14:17], v147 offset:9216
	ds_read_b128 v[204:207], v147 offset:9248
	ds_read_b128 v[208:211], v147 offset:13824
	ds_read_b128 v[212:215], v147 offset:13856
	s_waitcnt lgkmcnt(8)
	v_mfma_f32_32x32x16_bf16 v[98:113], v[2:5], v[6:9], 0
	s_waitcnt lgkmcnt(5)
	v_mfma_f32_32x32x16_bf16 v[82:97], v[2:5], v[10:13], 0
	s_waitcnt lgkmcnt(3)
	v_mfma_f32_32x32x16_bf16 v[50:65], v[2:5], v[14:17], 0
	s_waitcnt lgkmcnt(1)
	v_mfma_f32_32x32x16_bf16 v[18:33], v[2:5], v[208:211], 0
	ds_read_b128 v[2:5], v148 offset:4608
	ds_read_b128 v[224:227], v148 offset:4640
	s_waitcnt lgkmcnt(1)
;     ...
;   for (int kt = 0; kt < nk; ++kt) {
;     __syncthreads();
;     if (kt + 1 < nk) {
;       u16* aw = As0 + ((kt + 1) & 1) * 256 * LD;
;       u16* bw = Bs0 + ((kt + 1) & 1) * 256 * LD;
; #pragma unroll
;       for (int i = 0; i < 4; ++i) { *(u32x4*)(aw + (srow + 64 * i) * LD + skc * 8) = ra[i]; *(u32x4*)(bw + (srow + 64 * i) * LD + skc * 8) = rb[i]; }
;     }
;     if (kt + 2 < nk) {
; #pragma unroll
;       for (int i = 0; i < 4; ++i) { ra[i] = *(const u32x4*)(Ag + (size_t)(64 * i) * K + (kt + 2) * 64); rb[i] = *(const u32x4*)(Bg[i] + (kt + 2) * 64); }
;     }
;     __builtin_amdgcn_sched_barrier(0);
;     const u16* as = As0 + (kt & 1) * 256 * LD + (wr * 128 + l31) * LD + h * 8;
;     const u16* bs = Bs0 + (kt & 1) * 256 * LD + (wc * 64 + l31) * LD + h * 8;
;     if (domma)
; #pragma unroll
;     for (int ks = 0; ks < 4; ++ks) {
;       bf16x8 wf[2], xf[4];
; #pragma unroll
;       for (int ct = 0; ct < 2; ++ct) wf[ct] = *(const bf16x8*)(bs + ct * 32 * LD + ks * 16);
; #pragma unroll
;       for (int tt = 0; tt < 4; ++tt) xf[tt] = *(const bf16x8*)(as + tt * 32 * LD + ks * 16);
; #pragma unroll
;       for (int ct = 0; ct < 2; ++ct)
; #pragma unroll
;         for (int tt = 0; tt < 4; ++tt) acc[ct][tt] = __builtin_amdgcn_mfma_f32_32x32x16_bf16(wf[ct], xf[tt], acc[ct][tt], 0, 0, 0);
;     }
	v_mfma_f32_32x32x16_bf16 v[114:129], v[2:5], v[6:9], 0
	v_mfma_f32_32x32x16_bf16 v[66:81], v[2:5], v[10:13], 0
	v_mfma_f32_32x32x16_bf16 v[34:49], v[2:5], v[14:17], 0
	v_mfma_f32_32x32x16_bf16 v[2:17], v[2:5], v[208:211], 0
	v_mfma_f32_32x32x16_bf16 v[98:113], v[192:195], v[196:199], v[98:113]
	v_mfma_f32_32x32x16_bf16 v[82:97], v[192:195], v[200:203], v[82:97]
	v_mfma_f32_32x32x16_bf16 v[50:65], v[192:195], v[204:207], v[50:65]
	v_mfma_f32_32x32x16_bf16 v[18:33], v[192:195], v[212:215], v[18:33]
	s_waitcnt lgkmcnt(0)
	v_mfma_f32_32x32x16_bf16 v[114:129], v[224:227], v[196:199], v[114:129]
	v_mfma_f32_32x32x16_bf16 v[66:81], v[224:227], v[200:203], v[66:81]
	v_mfma_f32_32x32x16_bf16 v[34:49], v[224:227], v[204:207], v[34:49]
	ds_read_b128 v[192:195], v148 offset:64
	ds_read_b128 v[196:199], v147 offset:64
	ds_read_b128 v[200:203], v148 offset:96
	ds_read_b128 v[204:207], v147 offset:96
	v_mfma_f32_32x32x16_bf16 v[2:17], v[224:227], v[212:215], v[2:17]
	ds_read_b128 v[208:211], v147 offset:4672
	ds_read_b128 v[212:215], v147 offset:4704
	ds_read_b128 v[224:227], v147 offset:9280
	ds_read_b128 v[228:231], v147 offset:9312
	ds_read_b128 v[232:235], v147 offset:13888
	ds_read_b128 v[236:239], v147 offset:13920
	s_waitcnt lgkmcnt(8)
	v_mfma_f32_32x32x16_bf16 v[98:113], v[192:195], v[196:199], v[98:113]
	s_waitcnt lgkmcnt(5)
	v_mfma_f32_32x32x16_bf16 v[82:97], v[192:195], v[208:211], v[82:97]
	s_waitcnt lgkmcnt(3)
	v_mfma_f32_32x32x16_bf16 v[50:65], v[192:195], v[224:227], v[50:65]
	s_waitcnt lgkmcnt(1)
	v_mfma_f32_32x32x16_bf16 v[18:33], v[192:195], v[232:235], v[18:33]
	ds_read_b128 v[192:195], v148 offset:4672
	ds_read_b128 v[240:243], v148 offset:4704
	s_waitcnt lgkmcnt(1)
	v_mfma_f32_32x32x16_bf16 v[114:129], v[192:195], v[196:199], v[114:129]
	v_mfma_f32_32x32x16_bf16 v[66:81], v[192:195], v[208:211], v[66:81]
	v_mfma_f32_32x32x16_bf16 v[34:49], v[192:195], v[224:227], v[34:49]
	v_mfma_f32_32x32x16_bf16 v[2:17], v[192:195], v[232:235], v[2:17]
	v_mfma_f32_32x32x16_bf16 v[98:113], v[200:203], v[204:207], v[98:113]
	v_mfma_f32_32x32x16_bf16 v[82:97], v[200:203], v[212:215], v[82:97]
	v_mfma_f32_32x32x16_bf16 v[50:65], v[200:203], v[228:231], v[50:65]
	v_mfma_f32_32x32x16_bf16 v[18:33], v[200:203], v[236:239], v[18:33]
	s_waitcnt lgkmcnt(0)
	v_mfma_f32_32x32x16_bf16 v[114:129], v[240:243], v[204:207], v[114:129]
	v_mfma_f32_32x32x16_bf16 v[66:81], v[240:243], v[212:215], v[66:81]
	v_mfma_f32_32x32x16_bf16 v[34:49], v[240:243], v[228:231], v[34:49]
	v_mfma_f32_32x32x16_bf16 v[2:17], v[240:243], v[236:239], v[2:17]
	s_barrier
	global_load_dwordx4 v[192:195], v[144:145], off offset:384
	global_load_dwordx4 v[196:199], v[142:143], off offset:384
	global_load_dwordx4 v[200:203], v[138:139], off offset:384
	global_load_dwordx4 v[204:207], v[136:137], off offset:384
	global_load_dwordx4 v[208:211], v[140:141], off offset:384
	global_load_dwordx4 v[212:215], v[130:131], off offset:384
	global_load_dwordx4 v[224:227], v[134:135], off offset:384
	global_load_dwordx4 v[228:231], v[132:133], off offset:384
	s_waitcnt vmcnt(8)
	ds_write_b128 v149, v[188:191]
	ds_write_b128 v152, v[180:183]
	ds_write_b128 v149, v[184:187] offset:9216
	ds_write_b128 v152, v[176:179] offset:9216
	ds_write_b128 v149, v[172:175] offset:18432
	ds_write_b128 v152, v[164:167] offset:18432
	ds_write_b128 v149, v[168:171] offset:27648
	ds_write_b128 v152, v[160:163] offset:27648
	ds_read_b128 v[160:163], v148 offset:36864
	ds_read_b128 v[164:167], v147 offset:36864
	ds_read_b128 v[168:171], v148 offset:36896
	ds_read_b128 v[172:175], v147 offset:36896
	ds_read_b128 v[176:179], v147 offset:41472
	ds_read_b128 v[180:183], v147 offset:41504
	ds_read_b128 v[184:187], v147 offset:46080
	ds_read_b128 v[188:191], v147 offset:46112
	ds_read_b128 v[232:235], v147 offset:50688
	ds_read_b128 v[236:239], v147 offset:50720
	s_waitcnt lgkmcnt(8)
	v_mfma_f32_32x32x16_bf16 v[98:113], v[160:163], v[164:167], v[98:113]
	s_waitcnt lgkmcnt(5)
	v_mfma_f32_32x32x16_bf16 v[82:97], v[160:163], v[176:179], v[82:97]
	s_waitcnt lgkmcnt(3)
	v_mfma_f32_32x32x16_bf16 v[50:65], v[160:163], v[184:187], v[50:65]
	s_waitcnt lgkmcnt(1)
	v_mfma_f32_32x32x16_bf16 v[18:33], v[160:163], v[232:235], v[18:33]
	ds_read_b128 v[160:163], v148 offset:41472
	ds_read_b128 v[240:243], v148 offset:41504
	s_waitcnt lgkmcnt(1)
	v_mfma_f32_32x32x16_bf16 v[114:129], v[160:163], v[164:167], v[114:129]
	v_mfma_f32_32x32x16_bf16 v[66:81], v[160:163], v[176:179], v[66:81]
	v_mfma_f32_32x32x16_bf16 v[34:49], v[160:163], v[184:187], v[34:49]
	v_mfma_f32_32x32x16_bf16 v[2:17], v[160:163], v[232:235], v[2:17]
	v_mfma_f32_32x32x16_bf16 v[98:113], v[168:171], v[172:175], v[98:113]
	v_mfma_f32_32x32x16_bf16 v[82:97], v[168:171], v[180:183], v[82:97]
	v_mfma_f32_32x32x16_bf16 v[50:65], v[168:171], v[188:191], v[50:65]
	v_mfma_f32_32x32x16_bf16 v[18:33], v[168:171], v[236:239], v[18:33]
	s_waitcnt lgkmcnt(0)
	v_mfma_f32_32x32x16_bf16 v[114:129], v[240:243], v[172:175], v[114:129]
	ds_read_b128 v[160:163], v148 offset:36928
	ds_read_b128 v[164:167], v147 offset:36928
	ds_read_b128 v[168:171], v148 offset:36960
	ds_read_b128 v[172:175], v147 offset:36960
	v_mfma_f32_32x32x16_bf16 v[66:81], v[240:243], v[180:183], v[66:81]
	ds_read_b128 v[176:179], v147 offset:41536
	ds_read_b128 v[180:183], v147 offset:41568
	v_mfma_f32_32x32x16_bf16 v[34:49], v[240:243], v[188:191], v[34:49]
	ds_read_b128 v[184:187], v147 offset:46144
	ds_read_b128 v[188:191], v147 offset:46176
	v_mfma_f32_32x32x16_bf16 v[2:17], v[240:243], v[236:239], v[2:17]
	ds_read_b128 v[232:235], v147 offset:50752
	ds_read_b128 v[236:239], v147 offset:50784
	s_waitcnt lgkmcnt(8)
	v_mfma_f32_32x32x16_bf16 v[98:113], v[160:163], v[164:167], v[98:113]
	s_waitcnt lgkmcnt(5)
	v_mfma_f32_32x32x16_bf16 v[82:97], v[160:163], v[176:179], v[82:97]
	s_waitcnt lgkmcnt(3)
	v_mfma_f32_32x32x16_bf16 v[50:65], v[160:163], v[184:187], v[50:65]
	s_waitcnt lgkmcnt(1)
	v_mfma_f32_32x32x16_bf16 v[18:33], v[160:163], v[232:235], v[18:33]
	ds_read_b128 v[160:163], v148 offset:41536
	ds_read_b128 v[240:243], v148 offset:41568
	s_waitcnt lgkmcnt(1)
	v_mfma_f32_32x32x16_bf16 v[114:129], v[160:163], v[164:167], v[114:129]
	v_mfma_f32_32x32x16_bf16 v[66:81], v[160:163], v[176:179], v[66:81]
	v_mfma_f32_32x32x16_bf16 v[34:49], v[160:163], v[184:187], v[34:49]
	v_mfma_f32_32x32x16_bf16 v[2:17], v[160:163], v[232:235], v[2:17]
	v_mfma_f32_32x32x16_bf16 v[98:113], v[168:171], v[172:175], v[98:113]
	v_mfma_f32_32x32x16_bf16 v[82:97], v[168:171], v[180:183], v[82:97]
	v_mfma_f32_32x32x16_bf16 v[50:65], v[168:171], v[188:191], v[50:65]
	v_mfma_f32_32x32x16_bf16 v[18:33], v[168:171], v[236:239], v[18:33]
	s_waitcnt lgkmcnt(0)
	v_mfma_f32_32x32x16_bf16 v[114:129], v[240:243], v[172:175], v[114:129]
	v_mfma_f32_32x32x16_bf16 v[66:81], v[240:243], v[180:183], v[66:81]
	v_mfma_f32_32x32x16_bf16 v[34:49], v[240:243], v[188:191], v[34:49]
	v_mfma_f32_32x32x16_bf16 v[2:17], v[240:243], v[236:239], v[2:17]
	s_barrier
;     ...
;   for (int kt = 0; kt < nk; ++kt) {
;     __syncthreads();
;     if (kt + 1 < nk) {
;       u16* aw = As0 + ((kt + 1) & 1) * 256 * LD;
;       u16* bw = Bs0 + ((kt + 1) & 1) * 256 * LD;
; #pragma unroll
;       for (int i = 0; i < 4; ++i) { *(u32x4*)(aw + (srow + 64 * i) * LD + skc * 8) = ra[i]; *(u32x4*)(bw + (srow + 64 * i) * LD + skc * 8) = rb[i]; }
;     }
;     if (kt + 2 < nk) {
; #pragma unroll
;       for (int i = 0; i < 4; ++i) { ra[i] = *(const u32x4*)(Ag + (size_t)(64 * i) * K + (kt + 2) * 64); rb[i] = *(const u32x4*)(Bg[i] + (kt + 2) * 64); }
;     }
;     __builtin_amdgcn_sched_barrier(0);
;     const u16* as = As0 + (kt & 1) * 256 * LD + (wr * 128 + l31) * LD + h * 8;
;     const u16* bs = Bs0 + (kt & 1) * 256 * LD + (wc * 64 + l31) * LD + h * 8;
;     if (domma)
; #pragma unroll
;     for (int ks = 0; ks < 4; ++ks) {
;       bf16x8 wf[2], xf[4];
; #pragma unroll
;       for (int ct = 0; ct < 2; ++ct) wf[ct] = *(const bf16x8*)(bs + ct * 32 * LD + ks * 16);
; #pragma unroll
;       for (int tt = 0; tt < 4; ++tt) xf[tt] = *(const bf16x8*)(as + tt * 32 * LD + ks * 16);
; #pragma unroll
;       for (int ct = 0; ct < 2; ++ct)
; #pragma unroll
;         for (int tt = 0; tt < 4; ++tt) acc[ct][tt] = __builtin_amdgcn_mfma_f32_32x32x16_bf16(wf[ct], xf[tt], acc[ct][tt], 0, 0, 0);
;     }
	global_load_dwordx4 v[160:163], v[144:145], off offset:512
	global_load_dwordx4 v[164:167], v[142:143], off offset:512
	global_load_dwordx4 v[168:171], v[138:139], off offset:512
	global_load_dwordx4 v[172:175], v[136:137], off offset:512
	global_load_dwordx4 v[176:179], v[140:141], off offset:512
	global_load_dwordx4 v[180:183], v[130:131], off offset:512
	global_load_dwordx4 v[184:187], v[134:135], off offset:512
	global_load_dwordx4 v[188:191], v[132:133], off offset:512
	s_waitcnt vmcnt(8)
	ds_write_b128 v149, v[228:231] offset:36864
	ds_write_b128 v152, v[212:215] offset:36864
	ds_write_b128 v149, v[224:227] offset:46080
	ds_write_b128 v152, v[208:211] offset:46080
	ds_write_b128 v149, v[204:207] offset:55296
	ds_write_b128 v152, v[196:199] offset:55296
	ds_write_b128 v149, v[200:203] offset:64512
	ds_write_b128 v152, v[192:195] offset:64512
	ds_read_b128 v[192:195], v148
	ds_read_b128 v[196:199], v147
	ds_read_b128 v[200:203], v148 offset:32
	ds_read_b128 v[204:207], v147 offset:32
	ds_read_b128 v[208:211], v147 offset:4608
	ds_read_b128 v[212:215], v147 offset:4640
	ds_read_b128 v[224:227], v147 offset:9216
	ds_read_b128 v[228:231], v147 offset:9248
	ds_read_b128 v[232:235], v147 offset:13824
	ds_read_b128 v[236:239], v147 offset:13856
	s_waitcnt lgkmcnt(8)
	v_mfma_f32_32x32x16_bf16 v[98:113], v[192:195], v[196:199], v[98:113]
	s_waitcnt lgkmcnt(5)
	v_mfma_f32_32x32x16_bf16 v[82:97], v[192:195], v[208:211], v[82:97]
	s_waitcnt lgkmcnt(3)
	v_mfma_f32_32x32x16_bf16 v[50:65], v[192:195], v[224:227], v[50:65]
	s_waitcnt lgkmcnt(1)
	v_mfma_f32_32x32x16_bf16 v[18:33], v[192:195], v[232:235], v[18:33]
	ds_read_b128 v[192:195], v148 offset:4608
	ds_read_b128 v[240:243], v148 offset:4640
	s_waitcnt lgkmcnt(1)
	v_mfma_f32_32x32x16_bf16 v[114:129], v[192:195], v[196:199], v[114:129]
	v_mfma_f32_32x32x16_bf16 v[66:81], v[192:195], v[208:211], v[66:81]
	v_mfma_f32_32x32x16_bf16 v[34:49], v[192:195], v[224:227], v[34:49]
	v_mfma_f32_32x32x16_bf16 v[2:17], v[192:195], v[232:235], v[2:17]
	v_mfma_f32_32x32x16_bf16 v[98:113], v[200:203], v[204:207], v[98:113]
	v_mfma_f32_32x32x16_bf16 v[82:97], v[200:203], v[212:215], v[82:97]
	v_mfma_f32_32x32x16_bf16 v[50:65], v[200:203], v[228:231], v[50:65]
	v_mfma_f32_32x32x16_bf16 v[18:33], v[200:203], v[236:239], v[18:33]
	s_waitcnt lgkmcnt(0)
	v_mfma_f32_32x32x16_bf16 v[114:129], v[240:243], v[204:207], v[114:129]
	ds_read_b128 v[192:195], v148 offset:64
	ds_read_b128 v[196:199], v147 offset:64
	ds_read_b128 v[200:203], v148 offset:96
	ds_read_b128 v[204:207], v147 offset:96
	v_mfma_f32_32x32x16_bf16 v[66:81], v[240:243], v[212:215], v[66:81]
	ds_read_b128 v[208:211], v147 offset:4672
	ds_read_b128 v[212:215], v147 offset:4704
	v_mfma_f32_32x32x16_bf16 v[34:49], v[240:243], v[228:231], v[34:49]
	ds_read_b128 v[224:227], v147 offset:9280
	ds_read_b128 v[228:231], v147 offset:9312
	v_mfma_f32_32x32x16_bf16 v[2:17], v[240:243], v[236:239], v[2:17]
	ds_read_b128 v[232:235], v147 offset:13888
	ds_read_b128 v[236:239], v147 offset:13920
	s_waitcnt lgkmcnt(8)
	v_mfma_f32_32x32x16_bf16 v[98:113], v[192:195], v[196:199], v[98:113]
	s_waitcnt lgkmcnt(5)
	v_mfma_f32_32x32x16_bf16 v[82:97], v[192:195], v[208:211], v[82:97]
	s_waitcnt lgkmcnt(3)
	v_mfma_f32_32x32x16_bf16 v[50:65], v[192:195], v[224:227], v[50:65]
	s_waitcnt lgkmcnt(1)
	v_mfma_f32_32x32x16_bf16 v[18:33], v[192:195], v[232:235], v[18:33]
	ds_read_b128 v[192:195], v148 offset:4672
	ds_read_b128 v[240:243], v148 offset:4704
	s_waitcnt lgkmcnt(1)
	v_mfma_f32_32x32x16_bf16 v[114:129], v[192:195], v[196:199], v[114:129]
	v_mfma_f32_32x32x16_bf16 v[66:81], v[192:195], v[208:211], v[66:81]
	v_mfma_f32_32x32x16_bf16 v[34:49], v[192:195], v[224:227], v[34:49]
	v_mfma_f32_32x32x16_bf16 v[2:17], v[192:195], v[232:235], v[2:17]
	v_mfma_f32_32x32x16_bf16 v[98:113], v[200:203], v[204:207], v[98:113]
	v_mfma_f32_32x32x16_bf16 v[82:97], v[200:203], v[212:215], v[82:97]
	v_mfma_f32_32x32x16_bf16 v[50:65], v[200:203], v[228:231], v[50:65]
	v_mfma_f32_32x32x16_bf16 v[18:33], v[200:203], v[236:239], v[18:33]
	s_waitcnt lgkmcnt(0)
	v_mfma_f32_32x32x16_bf16 v[114:129], v[240:243], v[204:207], v[114:129]
	v_mfma_f32_32x32x16_bf16 v[66:81], v[240:243], v[212:215], v[66:81]
	v_mfma_f32_32x32x16_bf16 v[34:49], v[240:243], v[228:231], v[34:49]
	v_mfma_f32_32x32x16_bf16 v[2:17], v[240:243], v[236:239], v[2:17]
	s_barrier
;     ...
;   for (int kt = 0; kt < nk; ++kt) {
;     __syncthreads();
;     if (kt + 1 < nk) {
;       u16* aw = As0 + ((kt + 1) & 1) * 256 * LD;
;       u16* bw = Bs0 + ((kt + 1) & 1) * 256 * LD;
; #pragma unroll
;       for (int i = 0; i < 4; ++i) { *(u32x4*)(aw + (srow + 64 * i) * LD + skc * 8) = ra[i]; *(u32x4*)(bw + (srow + 64 * i) * LD + skc * 8) = rb[i]; }
;     }
;     if (kt + 2 < nk) {
; #pragma unroll
;       for (int i = 0; i < 4; ++i) { ra[i] = *(const u32x4*)(Ag + (size_t)(64 * i) * K + (kt + 2) * 64); rb[i] = *(const u32x4*)(Bg[i] + (kt + 2) * 64); }
;     }
;     __builtin_amdgcn_sched_barrier(0);
;     const u16* as = As0 + (kt & 1) * 256 * LD + (wr * 128 + l31) * LD + h * 8;
;     const u16* bs = Bs0 + (kt & 1) * 256 * LD + (wc * 64 + l31) * LD + h * 8;
;     if (domma)
; #pragma unroll
;     for (int ks = 0; ks < 4; ++ks) {
;       bf16x8 wf[2], xf[4];
; #pragma unroll
;       for (int ct = 0; ct < 2; ++ct) wf[ct] = *(const bf16x8*)(bs + ct * 32 * LD + ks * 16);
; #pragma unroll
;       for (int tt = 0; tt < 4; ++tt) xf[tt] = *(const bf16x8*)(as + tt * 32 * LD + ks * 16);
; #pragma unroll
;       for (int ct = 0; ct < 2; ++ct)
; #pragma unroll
;         for (int tt = 0; tt < 4; ++tt) acc[ct][tt] = __builtin_amdgcn_mfma_f32_32x32x16_bf16(wf[ct], xf[tt], acc[ct][tt], 0, 0, 0);
;     }
	global_load_dwordx4 v[192:195], v[144:145], off offset:640
	global_load_dwordx4 v[196:199], v[142:143], off offset:640
	global_load_dwordx4 v[200:203], v[138:139], off offset:640
	global_load_dwordx4 v[204:207], v[136:137], off offset:640
	global_load_dwordx4 v[208:211], v[140:141], off offset:640
	global_load_dwordx4 v[212:215], v[130:131], off offset:640
	global_load_dwordx4 v[224:227], v[134:135], off offset:640
	global_load_dwordx4 v[228:231], v[132:133], off offset:640
	s_waitcnt vmcnt(8)
	ds_write_b128 v149, v[188:191]
	ds_write_b128 v152, v[180:183]
	ds_write_b128 v149, v[184:187] offset:9216
	ds_write_b128 v152, v[176:179] offset:9216
	ds_write_b128 v149, v[172:175] offset:18432
	ds_write_b128 v152, v[164:167] offset:18432
	ds_write_b128 v149, v[168:171] offset:27648
	ds_write_b128 v152, v[160:163] offset:27648
	ds_read_b128 v[160:163], v148 offset:36864
	ds_read_b128 v[164:167], v147 offset:36864
	ds_read_b128 v[168:171], v148 offset:36896
	ds_read_b128 v[172:175], v147 offset:36896
	ds_read_b128 v[176:179], v147 offset:41472
	ds_read_b128 v[180:183], v147 offset:41504
	ds_read_b128 v[184:187], v147 offset:46080
	ds_read_b128 v[188:191], v147 offset:46112
	ds_read_b128 v[232:235], v147 offset:50688
	ds_read_b128 v[236:239], v147 offset:50720
	s_waitcnt lgkmcnt(8)
	v_mfma_f32_32x32x16_bf16 v[98:113], v[160:163], v[164:167], v[98:113]
	s_waitcnt lgkmcnt(5)
	v_mfma_f32_32x32x16_bf16 v[82:97], v[160:163], v[176:179], v[82:97]
	s_waitcnt lgkmcnt(3)
	v_mfma_f32_32x32x16_bf16 v[50:65], v[160:163], v[184:187], v[50:65]
	s_waitcnt lgkmcnt(1)
	v_mfma_f32_32x32x16_bf16 v[18:33], v[160:163], v[232:235], v[18:33]
	ds_read_b128 v[160:163], v148 offset:41472
	ds_read_b128 v[240:243], v148 offset:41504
	s_waitcnt lgkmcnt(1)
	v_mfma_f32_32x32x16_bf16 v[114:129], v[160:163], v[164:167], v[114:129]
	v_mfma_f32_32x32x16_bf16 v[66:81], v[160:163], v[176:179], v[66:81]
	v_mfma_f32_32x32x16_bf16 v[34:49], v[160:163], v[184:187], v[34:49]
	v_mfma_f32_32x32x16_bf16 v[2:17], v[160:163], v[232:235], v[2:17]
	v_mfma_f32_32x32x16_bf16 v[98:113], v[168:171], v[172:175], v[98:113]
	v_mfma_f32_32x32x16_bf16 v[82:97], v[168:171], v[180:183], v[82:97]
	v_mfma_f32_32x32x16_bf16 v[50:65], v[168:171], v[188:191], v[50:65]
	v_mfma_f32_32x32x16_bf16 v[18:33], v[168:171], v[236:239], v[18:33]
	s_waitcnt lgkmcnt(0)
	v_mfma_f32_32x32x16_bf16 v[114:129], v[240:243], v[172:175], v[114:129]
	ds_read_b128 v[160:163], v148 offset:36928
	ds_read_b128 v[164:167], v147 offset:36928
	ds_read_b128 v[168:171], v148 offset:36960
	ds_read_b128 v[172:175], v147 offset:36960
	v_mfma_f32_32x32x16_bf16 v[66:81], v[240:243], v[180:183], v[66:81]
	ds_read_b128 v[176:179], v147 offset:41536
	ds_read_b128 v[180:183], v147 offset:41568
	v_mfma_f32_32x32x16_bf16 v[34:49], v[240:243], v[188:191], v[34:49]
	ds_read_b128 v[184:187], v147 offset:46144
	ds_read_b128 v[188:191], v147 offset:46176
	v_mfma_f32_32x32x16_bf16 v[2:17], v[240:243], v[236:239], v[2:17]
	ds_read_b128 v[232:235], v147 offset:50752
	ds_read_b128 v[236:239], v147 offset:50784
	s_waitcnt lgkmcnt(8)
	v_mfma_f32_32x32x16_bf16 v[98:113], v[160:163], v[164:167], v[98:113]
	s_waitcnt lgkmcnt(5)
	v_mfma_f32_32x32x16_bf16 v[82:97], v[160:163], v[176:179], v[82:97]
	s_waitcnt lgkmcnt(3)
	v_mfma_f32_32x32x16_bf16 v[50:65], v[160:163], v[184:187], v[50:65]
	s_waitcnt lgkmcnt(1)
	v_mfma_f32_32x32x16_bf16 v[18:33], v[160:163], v[232:235], v[18:33]
	ds_read_b128 v[160:163], v148 offset:41536
	ds_read_b128 v[240:243], v148 offset:41568
	s_waitcnt lgkmcnt(1)
	v_mfma_f32_32x32x16_bf16 v[114:129], v[160:163], v[164:167], v[114:129]
	v_mfma_f32_32x32x16_bf16 v[66:81], v[160:163], v[176:179], v[66:81]
	v_mfma_f32_32x32x16_bf16 v[34:49], v[160:163], v[184:187], v[34:49]
	v_mfma_f32_32x32x16_bf16 v[2:17], v[160:163], v[232:235], v[2:17]
	v_mfma_f32_32x32x16_bf16 v[98:113], v[168:171], v[172:175], v[98:113]
	v_mfma_f32_32x32x16_bf16 v[82:97], v[168:171], v[180:183], v[82:97]
	v_mfma_f32_32x32x16_bf16 v[50:65], v[168:171], v[188:191], v[50:65]
	v_mfma_f32_32x32x16_bf16 v[18:33], v[168:171], v[236:239], v[18:33]
	s_waitcnt lgkmcnt(0)
	v_mfma_f32_32x32x16_bf16 v[114:129], v[240:243], v[172:175], v[114:129]
	v_mfma_f32_32x32x16_bf16 v[66:81], v[240:243], v[180:183], v[66:81]
	v_mfma_f32_32x32x16_bf16 v[34:49], v[240:243], v[188:191], v[34:49]
	v_mfma_f32_32x32x16_bf16 v[2:17], v[240:243], v[236:239], v[2:17]
	s_barrier
;     ...
;   for (int kt = 0; kt < nk; ++kt) {
;     __syncthreads();
;     if (kt + 1 < nk) {
;       u16* aw = As0 + ((kt + 1) & 1) * 256 * LD;
;       u16* bw = Bs0 + ((kt + 1) & 1) * 256 * LD;
; #pragma unroll
;       for (int i = 0; i < 4; ++i) { *(u32x4*)(aw + (srow + 64 * i) * LD + skc * 8) = ra[i]; *(u32x4*)(bw + (srow + 64 * i) * LD + skc * 8) = rb[i]; }
;     }
;     if (kt + 2 < nk) {
; #pragma unroll
;       for (int i = 0; i < 4; ++i) { ra[i] = *(const u32x4*)(Ag + (size_t)(64 * i) * K + (kt + 2) * 64); rb[i] = *(const u32x4*)(Bg[i] + (kt + 2) * 64); }
;     }
;     __builtin_amdgcn_sched_barrier(0);
;     const u16* as = As0 + (kt & 1) * 256 * LD + (wr * 128 + l31) * LD + h * 8;
;     const u16* bs = Bs0 + (kt & 1) * 256 * LD + (wc * 64 + l31) * LD + h * 8;
;     if (domma)
; #pragma unroll
;     for (int ks = 0; ks < 4; ++ks) {
;       bf16x8 wf[2], xf[4];
; #pragma unroll
;       for (int ct = 0; ct < 2; ++ct) wf[ct] = *(const bf16x8*)(bs + ct * 32 * LD + ks * 16);
; #pragma unroll
;       for (int tt = 0; tt < 4; ++tt) xf[tt] = *(const bf16x8*)(as + tt * 32 * LD + ks * 16);
; #pragma unroll
;       for (int ct = 0; ct < 2; ++ct)
; #pragma unroll
;         for (int tt = 0; tt < 4; ++tt) acc[ct][tt] = __builtin_amdgcn_mfma_f32_32x32x16_bf16(wf[ct], xf[tt], acc[ct][tt], 0, 0, 0);
;     }
	global_load_dwordx4 v[160:163], v[144:145], off offset:768
	global_load_dwordx4 v[164:167], v[142:143], off offset:768
	global_load_dwordx4 v[168:171], v[138:139], off offset:768
	global_load_dwordx4 v[172:175], v[136:137], off offset:768
	global_load_dwordx4 v[176:179], v[140:141], off offset:768
	global_load_dwordx4 v[180:183], v[130:131], off offset:768
	global_load_dwordx4 v[184:187], v[134:135], off offset:768
	global_load_dwordx4 v[188:191], v[132:133], off offset:768
	s_waitcnt vmcnt(8)
	ds_write_b128 v149, v[228:231] offset:36864
	ds_write_b128 v152, v[212:215] offset:36864
	ds_write_b128 v149, v[224:227] offset:46080
	ds_write_b128 v152, v[208:211] offset:46080
	ds_write_b128 v149, v[204:207] offset:55296
	ds_write_b128 v152, v[196:199] offset:55296
	ds_write_b128 v149, v[200:203] offset:64512
	ds_write_b128 v152, v[192:195] offset:64512
	ds_read_b128 v[192:195], v148
	ds_read_b128 v[196:199], v147
	ds_read_b128 v[200:203], v148 offset:32
	ds_read_b128 v[204:207], v147 offset:32
	ds_read_b128 v[208:211], v147 offset:4608
	ds_read_b128 v[212:215], v147 offset:4640
	ds_read_b128 v[224:227], v147 offset:9216
	ds_read_b128 v[228:231], v147 offset:9248
	ds_read_b128 v[232:235], v147 offset:13824
	ds_read_b128 v[236:239], v147 offset:13856
	s_waitcnt lgkmcnt(8)
	v_mfma_f32_32x32x16_bf16 v[98:113], v[192:195], v[196:199], v[98:113]
	s_waitcnt lgkmcnt(5)
	v_mfma_f32_32x32x16_bf16 v[82:97], v[192:195], v[208:211], v[82:97]
	s_waitcnt lgkmcnt(3)
	v_mfma_f32_32x32x16_bf16 v[50:65], v[192:195], v[224:227], v[50:65]
	s_waitcnt lgkmcnt(1)
	v_mfma_f32_32x32x16_bf16 v[18:33], v[192:195], v[232:235], v[18:33]
	ds_read_b128 v[192:195], v148 offset:4608
	ds_read_b128 v[240:243], v148 offset:4640
	s_waitcnt lgkmcnt(1)
	v_mfma_f32_32x32x16_bf16 v[114:129], v[192:195], v[196:199], v[114:129]
	v_mfma_f32_32x32x16_bf16 v[66:81], v[192:195], v[208:211], v[66:81]
	v_mfma_f32_32x32x16_bf16 v[34:49], v[192:195], v[224:227], v[34:49]
	v_mfma_f32_32x32x16_bf16 v[2:17], v[192:195], v[232:235], v[2:17]
	v_mfma_f32_32x32x16_bf16 v[98:113], v[200:203], v[204:207], v[98:113]
	v_mfma_f32_32x32x16_bf16 v[82:97], v[200:203], v[212:215], v[82:97]
	v_mfma_f32_32x32x16_bf16 v[50:65], v[200:203], v[228:231], v[50:65]
	v_mfma_f32_32x32x16_bf16 v[18:33], v[200:203], v[236:239], v[18:33]
	s_waitcnt lgkmcnt(0)
	v_mfma_f32_32x32x16_bf16 v[114:129], v[240:243], v[204:207], v[114:129]
	ds_read_b128 v[192:195], v148 offset:64
	ds_read_b128 v[196:199], v147 offset:64
	ds_read_b128 v[200:203], v148 offset:96
	ds_read_b128 v[204:207], v147 offset:96
	v_mfma_f32_32x32x16_bf16 v[66:81], v[240:243], v[212:215], v[66:81]
	ds_read_b128 v[208:211], v147 offset:4672
	ds_read_b128 v[212:215], v147 offset:4704
	v_mfma_f32_32x32x16_bf16 v[34:49], v[240:243], v[228:231], v[34:49]
	ds_read_b128 v[224:227], v147 offset:9280
	ds_read_b128 v[228:231], v147 offset:9312
	v_mfma_f32_32x32x16_bf16 v[2:17], v[240:243], v[236:239], v[2:17]
	ds_read_b128 v[232:235], v147 offset:13888
	ds_read_b128 v[236:239], v147 offset:13920
	s_waitcnt lgkmcnt(8)
	v_mfma_f32_32x32x16_bf16 v[98:113], v[192:195], v[196:199], v[98:113]
	s_waitcnt lgkmcnt(5)
	v_mfma_f32_32x32x16_bf16 v[82:97], v[192:195], v[208:211], v[82:97]
	s_waitcnt lgkmcnt(3)
	v_mfma_f32_32x32x16_bf16 v[50:65], v[192:195], v[224:227], v[50:65]
	s_waitcnt lgkmcnt(1)
	v_mfma_f32_32x32x16_bf16 v[18:33], v[192:195], v[232:235], v[18:33]
	ds_read_b128 v[192:195], v148 offset:4672
	ds_read_b128 v[240:243], v148 offset:4704
	s_waitcnt lgkmcnt(1)
	v_mfma_f32_32x32x16_bf16 v[114:129], v[192:195], v[196:199], v[114:129]
	v_mfma_f32_32x32x16_bf16 v[66:81], v[192:195], v[208:211], v[66:81]
	v_mfma_f32_32x32x16_bf16 v[34:49], v[192:195], v[224:227], v[34:49]
	v_mfma_f32_32x32x16_bf16 v[2:17], v[192:195], v[232:235], v[2:17]
	v_mfma_f32_32x32x16_bf16 v[98:113], v[200:203], v[204:207], v[98:113]
	v_mfma_f32_32x32x16_bf16 v[82:97], v[200:203], v[212:215], v[82:97]
	v_mfma_f32_32x32x16_bf16 v[50:65], v[200:203], v[228:231], v[50:65]
	v_mfma_f32_32x32x16_bf16 v[18:33], v[200:203], v[236:239], v[18:33]
	s_waitcnt lgkmcnt(0)
	v_mfma_f32_32x32x16_bf16 v[114:129], v[240:243], v[204:207], v[114:129]
	v_mfma_f32_32x32x16_bf16 v[66:81], v[240:243], v[212:215], v[66:81]
	v_mfma_f32_32x32x16_bf16 v[34:49], v[240:243], v[228:231], v[34:49]
	v_mfma_f32_32x32x16_bf16 v[2:17], v[240:243], v[236:239], v[2:17]
	s_barrier
;     ...
;   for (int kt = 0; kt < nk; ++kt) {
;     __syncthreads();
;     if (kt + 1 < nk) {
;       u16* aw = As0 + ((kt + 1) & 1) * 256 * LD;
;       u16* bw = Bs0 + ((kt + 1) & 1) * 256 * LD;
; #pragma unroll
;       for (int i = 0; i < 4; ++i) { *(u32x4*)(aw + (srow + 64 * i) * LD + skc * 8) = ra[i]; *(u32x4*)(bw + (srow + 64 * i) * LD + skc * 8) = rb[i]; }
;     }
;     if (kt + 2 < nk) {
; #pragma unroll
;       for (int i = 0; i < 4; ++i) { ra[i] = *(const u32x4*)(Ag + (size_t)(64 * i) * K + (kt + 2) * 64); rb[i] = *(const u32x4*)(Bg[i] + (kt + 2) * 64); }
;     }
;     __builtin_amdgcn_sched_barrier(0);
;     const u16* as = As0 + (kt & 1) * 256 * LD + (wr * 128 + l31) * LD + h * 8;
;     const u16* bs = Bs0 + (kt & 1) * 256 * LD + (wc * 64 + l31) * LD + h * 8;
;     if (domma)
; #pragma unroll
;     for (int ks = 0; ks < 4; ++ks) {
;       bf16x8 wf[2], xf[4];
; #pragma unroll
;       for (int ct = 0; ct < 2; ++ct) wf[ct] = *(const bf16x8*)(bs + ct * 32 * LD + ks * 16);
; #pragma unroll
;       for (int tt = 0; tt < 4; ++tt) xf[tt] = *(const bf16x8*)(as + tt * 32 * LD + ks * 16);
; #pragma unroll
;       for (int ct = 0; ct < 2; ++ct)
; #pragma unroll
;         for (int tt = 0; tt < 4; ++tt) acc[ct][tt] = __builtin_amdgcn_mfma_f32_32x32x16_bf16(wf[ct], xf[tt], acc[ct][tt], 0, 0, 0);
;     }
	global_load_dwordx4 v[192:195], v[144:145], off offset:896
	global_load_dwordx4 v[196:199], v[142:143], off offset:896
	global_load_dwordx4 v[200:203], v[138:139], off offset:896
	global_load_dwordx4 v[204:207], v[136:137], off offset:896
	global_load_dwordx4 v[208:211], v[140:141], off offset:896
	global_load_dwordx4 v[212:215], v[130:131], off offset:896
	global_load_dwordx4 v[224:227], v[134:135], off offset:896
	global_load_dwordx4 v[228:231], v[132:133], off offset:896
	s_waitcnt vmcnt(8)
	ds_write_b128 v149, v[188:191]
	ds_write_b128 v152, v[180:183]
	ds_write_b128 v149, v[184:187] offset:9216
	ds_write_b128 v152, v[176:179] offset:9216
	ds_write_b128 v149, v[172:175] offset:18432
	ds_write_b128 v152, v[164:167] offset:18432
	ds_write_b128 v149, v[168:171] offset:27648
	ds_write_b128 v152, v[160:163] offset:27648
	ds_read_b128 v[160:163], v148 offset:36864
	ds_read_b128 v[164:167], v147 offset:36864
	ds_read_b128 v[168:171], v148 offset:36896
	ds_read_b128 v[172:175], v147 offset:36896
	ds_read_b128 v[176:179], v147 offset:41472
	ds_read_b128 v[180:183], v147 offset:41504
	ds_read_b128 v[184:187], v147 offset:46080
	ds_read_b128 v[188:191], v147 offset:46112
	ds_read_b128 v[232:235], v147 offset:50688
	ds_read_b128 v[236:239], v147 offset:50720
	s_waitcnt lgkmcnt(8)
	v_mfma_f32_32x32x16_bf16 v[98:113], v[160:163], v[164:167], v[98:113]
	s_waitcnt lgkmcnt(5)
	v_mfma_f32_32x32x16_bf16 v[82:97], v[160:163], v[176:179], v[82:97]
	s_waitcnt lgkmcnt(3)
	v_mfma_f32_32x32x16_bf16 v[50:65], v[160:163], v[184:187], v[50:65]
	s_waitcnt lgkmcnt(1)
	v_mfma_f32_32x32x16_bf16 v[18:33], v[160:163], v[232:235], v[18:33]
	ds_read_b128 v[160:163], v148 offset:41472
	ds_read_b128 v[240:243], v148 offset:41504
	s_waitcnt lgkmcnt(1)
	v_mfma_f32_32x32x16_bf16 v[114:129], v[160:163], v[164:167], v[114:129]
	v_mfma_f32_32x32x16_bf16 v[66:81], v[160:163], v[176:179], v[66:81]
	v_mfma_f32_32x32x16_bf16 v[34:49], v[160:163], v[184:187], v[34:49]
	v_mfma_f32_32x32x16_bf16 v[2:17], v[160:163], v[232:235], v[2:17]
	v_mfma_f32_32x32x16_bf16 v[98:113], v[168:171], v[172:175], v[98:113]
	v_mfma_f32_32x32x16_bf16 v[82:97], v[168:171], v[180:183], v[82:97]
	v_mfma_f32_32x32x16_bf16 v[50:65], v[168:171], v[188:191], v[50:65]
	v_mfma_f32_32x32x16_bf16 v[18:33], v[168:171], v[236:239], v[18:33]
	s_waitcnt lgkmcnt(0)
	v_mfma_f32_32x32x16_bf16 v[114:129], v[240:243], v[172:175], v[114:129]
	ds_read_b128 v[160:163], v148 offset:36928
	ds_read_b128 v[164:167], v147 offset:36928
	ds_read_b128 v[168:171], v148 offset:36960
	ds_read_b128 v[172:175], v147 offset:36960
	v_mfma_f32_32x32x16_bf16 v[66:81], v[240:243], v[180:183], v[66:81]
	ds_read_b128 v[176:179], v147 offset:41536
	ds_read_b128 v[180:183], v147 offset:41568
	v_mfma_f32_32x32x16_bf16 v[34:49], v[240:243], v[188:191], v[34:49]
	ds_read_b128 v[184:187], v147 offset:46144
	ds_read_b128 v[188:191], v147 offset:46176
	v_mfma_f32_32x32x16_bf16 v[2:17], v[240:243], v[236:239], v[2:17]
	ds_read_b128 v[232:235], v147 offset:50752
	ds_read_b128 v[236:239], v147 offset:50784
	s_waitcnt lgkmcnt(8)
	v_mfma_f32_32x32x16_bf16 v[98:113], v[160:163], v[164:167], v[98:113]
	s_waitcnt lgkmcnt(5)
	v_mfma_f32_32x32x16_bf16 v[82:97], v[160:163], v[176:179], v[82:97]
	s_waitcnt lgkmcnt(3)
	v_mfma_f32_32x32x16_bf16 v[50:65], v[160:163], v[184:187], v[50:65]
	s_waitcnt lgkmcnt(1)
	v_mfma_f32_32x32x16_bf16 v[18:33], v[160:163], v[232:235], v[18:33]
	ds_read_b128 v[160:163], v148 offset:41536
	ds_read_b128 v[240:243], v148 offset:41568
	s_waitcnt lgkmcnt(1)
	v_mfma_f32_32x32x16_bf16 v[114:129], v[160:163], v[164:167], v[114:129]
	v_mfma_f32_32x32x16_bf16 v[66:81], v[160:163], v[176:179], v[66:81]
	v_mfma_f32_32x32x16_bf16 v[34:49], v[160:163], v[184:187], v[34:49]
	v_mfma_f32_32x32x16_bf16 v[2:17], v[160:163], v[232:235], v[2:17]
	v_mfma_f32_32x32x16_bf16 v[98:113], v[168:171], v[172:175], v[98:113]
	v_mfma_f32_32x32x16_bf16 v[82:97], v[168:171], v[180:183], v[82:97]
	v_mfma_f32_32x32x16_bf16 v[50:65], v[168:171], v[188:191], v[50:65]
	v_mfma_f32_32x32x16_bf16 v[18:33], v[168:171], v[236:239], v[18:33]
	s_waitcnt lgkmcnt(0)
	v_mfma_f32_32x32x16_bf16 v[114:129], v[240:243], v[172:175], v[114:129]
	v_mfma_f32_32x32x16_bf16 v[66:81], v[240:243], v[180:183], v[66:81]
	v_mfma_f32_32x32x16_bf16 v[34:49], v[240:243], v[188:191], v[34:49]
	v_mfma_f32_32x32x16_bf16 v[2:17], v[240:243], v[236:239], v[2:17]
	s_barrier
;     ...
;   for (int kt = 0; kt < nk; ++kt) {
;     __syncthreads();
;     if (kt + 1 < nk) {
;       u16* aw = As0 + ((kt + 1) & 1) * 256 * LD;
;       u16* bw = Bs0 + ((kt + 1) & 1) * 256 * LD;
; #pragma unroll
;       for (int i = 0; i < 4; ++i) { *(u32x4*)(aw + (srow + 64 * i) * LD + skc * 8) = ra[i]; *(u32x4*)(bw + (srow + 64 * i) * LD + skc * 8) = rb[i]; }
;     }
;     if (kt + 2 < nk) {
; #pragma unroll
;       for (int i = 0; i < 4; ++i) { ra[i] = *(const u32x4*)(Ag + (size_t)(64 * i) * K + (kt + 2) * 64); rb[i] = *(const u32x4*)(Bg[i] + (kt + 2) * 64); }
;     }
;     __builtin_amdgcn_sched_barrier(0);
;     const u16* as = As0 + (kt & 1) * 256 * LD + (wr * 128 + l31) * LD + h * 8;
;     const u16* bs = Bs0 + (kt & 1) * 256 * LD + (wc * 64 + l31) * LD + h * 8;
;     if (domma)
; #pragma unroll
;     for (int ks = 0; ks < 4; ++ks) {
;       bf16x8 wf[2], xf[4];
; #pragma unroll
;       for (int ct = 0; ct < 2; ++ct) wf[ct] = *(const bf16x8*)(bs + ct * 32 * LD + ks * 16);
; #pragma unroll
;       for (int tt = 0; tt < 4; ++tt) xf[tt] = *(const bf16x8*)(as + tt * 32 * LD + ks * 16);
; #pragma unroll
;       for (int ct = 0; ct < 2; ++ct)
; #pragma unroll
;         for (int tt = 0; tt < 4; ++tt) acc[ct][tt] = __builtin_amdgcn_mfma_f32_32x32x16_bf16(wf[ct], xf[tt], acc[ct][tt], 0, 0, 0);
;     }
	global_load_dwordx4 v[160:163], v[144:145], off offset:1024
	global_load_dwordx4 v[164:167], v[142:143], off offset:1024
	global_load_dwordx4 v[168:171], v[138:139], off offset:1024
	global_load_dwordx4 v[172:175], v[136:137], off offset:1024
	global_load_dwordx4 v[176:179], v[140:141], off offset:1024
	global_load_dwordx4 v[180:183], v[130:131], off offset:1024
	global_load_dwordx4 v[184:187], v[134:135], off offset:1024
	global_load_dwordx4 v[188:191], v[132:133], off offset:1024
	s_waitcnt vmcnt(8)
	ds_write_b128 v149, v[228:231] offset:36864
	ds_write_b128 v152, v[212:215] offset:36864
	ds_write_b128 v149, v[224:227] offset:46080
	ds_write_b128 v152, v[208:211] offset:46080
	ds_write_b128 v149, v[204:207] offset:55296
	ds_write_b128 v152, v[196:199] offset:55296
	ds_write_b128 v149, v[200:203] offset:64512
	ds_write_b128 v152, v[192:195] offset:64512
	ds_read_b128 v[192:195], v148
	ds_read_b128 v[196:199], v147
	ds_read_b128 v[200:203], v148 offset:32
	ds_read_b128 v[204:207], v147 offset:32
	ds_read_b128 v[208:211], v147 offset:4608
	ds_read_b128 v[212:215], v147 offset:4640
	ds_read_b128 v[224:227], v147 offset:9216
	ds_read_b128 v[228:231], v147 offset:9248
	ds_read_b128 v[232:235], v147 offset:13824
	ds_read_b128 v[236:239], v147 offset:13856
	s_waitcnt lgkmcnt(8)
	v_mfma_f32_32x32x16_bf16 v[98:113], v[192:195], v[196:199], v[98:113]
	s_waitcnt lgkmcnt(5)
	v_mfma_f32_32x32x16_bf16 v[82:97], v[192:195], v[208:211], v[82:97]
	s_waitcnt lgkmcnt(3)
	v_mfma_f32_32x32x16_bf16 v[50:65], v[192:195], v[224:227], v[50:65]
	s_waitcnt lgkmcnt(1)
	v_mfma_f32_32x32x16_bf16 v[18:33], v[192:195], v[232:235], v[18:33]
	ds_read_b128 v[192:195], v148 offset:4608
	ds_read_b128 v[240:243], v148 offset:4640
	s_waitcnt lgkmcnt(1)
	v_mfma_f32_32x32x16_bf16 v[114:129], v[192:195], v[196:199], v[114:129]
	v_mfma_f32_32x32x16_bf16 v[66:81], v[192:195], v[208:211], v[66:81]
	v_mfma_f32_32x32x16_bf16 v[34:49], v[192:195], v[224:227], v[34:49]
	v_mfma_f32_32x32x16_bf16 v[2:17], v[192:195], v[232:235], v[2:17]
	v_mfma_f32_32x32x16_bf16 v[98:113], v[200:203], v[204:207], v[98:113]
	v_mfma_f32_32x32x16_bf16 v[82:97], v[200:203], v[212:215], v[82:97]
	v_mfma_f32_32x32x16_bf16 v[50:65], v[200:203], v[228:231], v[50:65]
	v_mfma_f32_32x32x16_bf16 v[18:33], v[200:203], v[236:239], v[18:33]
	s_waitcnt lgkmcnt(0)
	v_mfma_f32_32x32x16_bf16 v[114:129], v[240:243], v[204:207], v[114:129]
	ds_read_b128 v[192:195], v148 offset:64
	ds_read_b128 v[196:199], v147 offset:64
	ds_read_b128 v[200:203], v148 offset:96
	ds_read_b128 v[204:207], v147 offset:96
	v_mfma_f32_32x32x16_bf16 v[66:81], v[240:243], v[212:215], v[66:81]
	ds_read_b128 v[208:211], v147 offset:4672
	ds_read_b128 v[212:215], v147 offset:4704
	v_mfma_f32_32x32x16_bf16 v[34:49], v[240:243], v[228:231], v[34:49]
	ds_read_b128 v[224:227], v147 offset:9280
	ds_read_b128 v[228:231], v147 offset:9312
	v_mfma_f32_32x32x16_bf16 v[2:17], v[240:243], v[236:239], v[2:17]
	ds_read_b128 v[232:235], v147 offset:13888
	ds_read_b128 v[236:239], v147 offset:13920
	s_waitcnt lgkmcnt(8)
	v_mfma_f32_32x32x16_bf16 v[98:113], v[192:195], v[196:199], v[98:113]
	s_waitcnt lgkmcnt(5)
	v_mfma_f32_32x32x16_bf16 v[82:97], v[192:195], v[208:211], v[82:97]
	s_waitcnt lgkmcnt(3)
	v_mfma_f32_32x32x16_bf16 v[50:65], v[192:195], v[224:227], v[50:65]
	s_waitcnt lgkmcnt(1)
	v_mfma_f32_32x32x16_bf16 v[18:33], v[192:195], v[232:235], v[18:33]
	ds_read_b128 v[192:195], v148 offset:4672
	ds_read_b128 v[240:243], v148 offset:4704
	s_waitcnt lgkmcnt(1)
	v_mfma_f32_32x32x16_bf16 v[114:129], v[192:195], v[196:199], v[114:129]
	v_mfma_f32_32x32x16_bf16 v[66:81], v[192:195], v[208:211], v[66:81]
	v_mfma_f32_32x32x16_bf16 v[34:49], v[192:195], v[224:227], v[34:49]
	v_mfma_f32_32x32x16_bf16 v[2:17], v[192:195], v[232:235], v[2:17]
	v_mfma_f32_32x32x16_bf16 v[98:113], v[200:203], v[204:207], v[98:113]
	v_mfma_f32_32x32x16_bf16 v[82:97], v[200:203], v[212:215], v[82:97]
	v_mfma_f32_32x32x16_bf16 v[50:65], v[200:203], v[228:231], v[50:65]
	v_mfma_f32_32x32x16_bf16 v[18:33], v[200:203], v[236:239], v[18:33]
	s_waitcnt lgkmcnt(0)
	v_mfma_f32_32x32x16_bf16 v[114:129], v[240:243], v[204:207], v[114:129]
	v_mfma_f32_32x32x16_bf16 v[66:81], v[240:243], v[212:215], v[66:81]
	v_mfma_f32_32x32x16_bf16 v[34:49], v[240:243], v[228:231], v[34:49]
	v_mfma_f32_32x32x16_bf16 v[2:17], v[240:243], v[236:239], v[2:17]
	s_barrier
;     ...
;   for (int kt = 0; kt < nk; ++kt) {
;     __syncthreads();
;     if (kt + 1 < nk) {
;       u16* aw = As0 + ((kt + 1) & 1) * 256 * LD;
;       u16* bw = Bs0 + ((kt + 1) & 1) * 256 * LD;
; #pragma unroll
;       for (int i = 0; i < 4; ++i) { *(u32x4*)(aw + (srow + 64 * i) * LD + skc * 8) = ra[i]; *(u32x4*)(bw + (srow + 64 * i) * LD + skc * 8) = rb[i]; }
;     }
;     if (kt + 2 < nk) {
; #pragma unroll
;       for (int i = 0; i < 4; ++i) { ra[i] = *(const u32x4*)(Ag + (size_t)(64 * i) * K + (kt + 2) * 64); rb[i] = *(const u32x4*)(Bg[i] + (kt + 2) * 64); }
;     }
;     __builtin_amdgcn_sched_barrier(0);
;     const u16* as = As0 + (kt & 1) * 256 * LD + (wr * 128 + l31) * LD + h * 8;
;     const u16* bs = Bs0 + (kt & 1) * 256 * LD + (wc * 64 + l31) * LD + h * 8;
;     if (domma)
; #pragma unroll
;     for (int ks = 0; ks < 4; ++ks) {
;       bf16x8 wf[2], xf[4];
; #pragma unroll
;       for (int ct = 0; ct < 2; ++ct) wf[ct] = *(const bf16x8*)(bs + ct * 32 * LD + ks * 16);
; #pragma unroll
;       for (int tt = 0; tt < 4; ++tt) xf[tt] = *(const bf16x8*)(as + tt * 32 * LD + ks * 16);
; #pragma unroll
;       for (int ct = 0; ct < 2; ++ct)
; #pragma unroll
;         for (int tt = 0; tt < 4; ++tt) acc[ct][tt] = __builtin_amdgcn_mfma_f32_32x32x16_bf16(wf[ct], xf[tt], acc[ct][tt], 0, 0, 0);
;     }
	global_load_dwordx4 v[192:195], v[144:145], off offset:1152
	global_load_dwordx4 v[196:199], v[142:143], off offset:1152
	global_load_dwordx4 v[200:203], v[138:139], off offset:1152
	global_load_dwordx4 v[204:207], v[136:137], off offset:1152
	global_load_dwordx4 v[208:211], v[140:141], off offset:1152
	global_load_dwordx4 v[212:215], v[130:131], off offset:1152
	global_load_dwordx4 v[224:227], v[134:135], off offset:1152
	global_load_dwordx4 v[228:231], v[132:133], off offset:1152
	s_waitcnt vmcnt(8)
	ds_write_b128 v149, v[188:191]
	ds_write_b128 v152, v[180:183]
	ds_write_b128 v149, v[184:187] offset:9216
	ds_write_b128 v152, v[176:179] offset:9216
	ds_write_b128 v149, v[172:175] offset:18432
	ds_write_b128 v152, v[164:167] offset:18432
	ds_write_b128 v149, v[168:171] offset:27648
	ds_write_b128 v152, v[160:163] offset:27648
	ds_read_b128 v[160:163], v148 offset:36864
	ds_read_b128 v[164:167], v147 offset:36864
	ds_read_b128 v[168:171], v148 offset:36896
	ds_read_b128 v[172:175], v147 offset:36896
	ds_read_b128 v[176:179], v147 offset:41472
	ds_read_b128 v[180:183], v147 offset:41504
	ds_read_b128 v[184:187], v147 offset:46080
	ds_read_b128 v[188:191], v147 offset:46112
	ds_read_b128 v[232:235], v147 offset:50688
	ds_read_b128 v[236:239], v147 offset:50720
	s_waitcnt lgkmcnt(8)
	v_mfma_f32_32x32x16_bf16 v[98:113], v[160:163], v[164:167], v[98:113]
	s_waitcnt lgkmcnt(5)
	v_mfma_f32_32x32x16_bf16 v[82:97], v[160:163], v[176:179], v[82:97]
	s_waitcnt lgkmcnt(3)
	v_mfma_f32_32x32x16_bf16 v[50:65], v[160:163], v[184:187], v[50:65]
	s_waitcnt lgkmcnt(1)
	v_mfma_f32_32x32x16_bf16 v[18:33], v[160:163], v[232:235], v[18:33]
	ds_read_b128 v[160:163], v148 offset:41472
	ds_read_b128 v[240:243], v148 offset:41504
	s_waitcnt lgkmcnt(1)
	v_mfma_f32_32x32x16_bf16 v[114:129], v[160:163], v[164:167], v[114:129]
	v_mfma_f32_32x32x16_bf16 v[66:81], v[160:163], v[176:179], v[66:81]
	v_mfma_f32_32x32x16_bf16 v[34:49], v[160:163], v[184:187], v[34:49]
	v_mfma_f32_32x32x16_bf16 v[2:17], v[160:163], v[232:235], v[2:17]
	v_mfma_f32_32x32x16_bf16 v[98:113], v[168:171], v[172:175], v[98:113]
	v_mfma_f32_32x32x16_bf16 v[82:97], v[168:171], v[180:183], v[82:97]
	v_mfma_f32_32x32x16_bf16 v[50:65], v[168:171], v[188:191], v[50:65]
	v_mfma_f32_32x32x16_bf16 v[18:33], v[168:171], v[236:239], v[18:33]
	s_waitcnt lgkmcnt(0)
	v_mfma_f32_32x32x16_bf16 v[114:129], v[240:243], v[172:175], v[114:129]
	ds_read_b128 v[160:163], v148 offset:36928
	ds_read_b128 v[164:167], v147 offset:36928
	ds_read_b128 v[168:171], v148 offset:36960
	ds_read_b128 v[172:175], v147 offset:36960
	v_mfma_f32_32x32x16_bf16 v[66:81], v[240:243], v[180:183], v[66:81]
	ds_read_b128 v[176:179], v147 offset:41536
	ds_read_b128 v[180:183], v147 offset:41568
	v_mfma_f32_32x32x16_bf16 v[34:49], v[240:243], v[188:191], v[34:49]
	ds_read_b128 v[184:187], v147 offset:46144
	ds_read_b128 v[188:191], v147 offset:46176
	v_mfma_f32_32x32x16_bf16 v[2:17], v[240:243], v[236:239], v[2:17]
	ds_read_b128 v[232:235], v147 offset:50752
	ds_read_b128 v[236:239], v147 offset:50784
	s_waitcnt lgkmcnt(8)
	v_mfma_f32_32x32x16_bf16 v[98:113], v[160:163], v[164:167], v[98:113]
	s_waitcnt lgkmcnt(5)
	v_mfma_f32_32x32x16_bf16 v[82:97], v[160:163], v[176:179], v[82:97]
	s_waitcnt lgkmcnt(3)
	v_mfma_f32_32x32x16_bf16 v[50:65], v[160:163], v[184:187], v[50:65]
	s_waitcnt lgkmcnt(1)
	v_mfma_f32_32x32x16_bf16 v[18:33], v[160:163], v[232:235], v[18:33]
	ds_read_b128 v[160:163], v148 offset:41536
	ds_read_b128 v[240:243], v148 offset:41568
	s_waitcnt lgkmcnt(1)
	v_mfma_f32_32x32x16_bf16 v[114:129], v[160:163], v[164:167], v[114:129]
	v_mfma_f32_32x32x16_bf16 v[66:81], v[160:163], v[176:179], v[66:81]
	v_mfma_f32_32x32x16_bf16 v[34:49], v[160:163], v[184:187], v[34:49]
	v_mfma_f32_32x32x16_bf16 v[2:17], v[160:163], v[232:235], v[2:17]
	v_mfma_f32_32x32x16_bf16 v[98:113], v[168:171], v[172:175], v[98:113]
	v_mfma_f32_32x32x16_bf16 v[82:97], v[168:171], v[180:183], v[82:97]
	v_mfma_f32_32x32x16_bf16 v[50:65], v[168:171], v[188:191], v[50:65]
	v_mfma_f32_32x32x16_bf16 v[18:33], v[168:171], v[236:239], v[18:33]
	s_waitcnt lgkmcnt(0)
	v_mfma_f32_32x32x16_bf16 v[114:129], v[240:243], v[172:175], v[114:129]
	v_mfma_f32_32x32x16_bf16 v[66:81], v[240:243], v[180:183], v[66:81]
	v_mfma_f32_32x32x16_bf16 v[34:49], v[240:243], v[188:191], v[34:49]
	v_mfma_f32_32x32x16_bf16 v[2:17], v[240:243], v[236:239], v[2:17]
	s_barrier
;     ...
;   for (int kt = 0; kt < nk; ++kt) {
;     __syncthreads();
;     if (kt + 1 < nk) {
;       u16* aw = As0 + ((kt + 1) & 1) * 256 * LD;
;       u16* bw = Bs0 + ((kt + 1) & 1) * 256 * LD;
; #pragma unroll
;       for (int i = 0; i < 4; ++i) { *(u32x4*)(aw + (srow + 64 * i) * LD + skc * 8) = ra[i]; *(u32x4*)(bw + (srow + 64 * i) * LD + skc * 8) = rb[i]; }
;     }
;     if (kt + 2 < nk) {
; #pragma unroll
;       for (int i = 0; i < 4; ++i) { ra[i] = *(const u32x4*)(Ag + (size_t)(64 * i) * K + (kt + 2) * 64); rb[i] = *(const u32x4*)(Bg[i] + (kt + 2) * 64); }
;     }
;     __builtin_amdgcn_sched_barrier(0);
;     const u16* as = As0 + (kt & 1) * 256 * LD + (wr * 128 + l31) * LD + h * 8;
;     const u16* bs = Bs0 + (kt & 1) * 256 * LD + (wc * 64 + l31) * LD + h * 8;
;     if (domma)
; #pragma unroll
;     for (int ks = 0; ks < 4; ++ks) {
;       bf16x8 wf[2], xf[4];
; #pragma unroll
;       for (int ct = 0; ct < 2; ++ct) wf[ct] = *(const bf16x8*)(bs + ct * 32 * LD + ks * 16);
; #pragma unroll
;       for (int tt = 0; tt < 4; ++tt) xf[tt] = *(const bf16x8*)(as + tt * 32 * LD + ks * 16);
; #pragma unroll
;       for (int ct = 0; ct < 2; ++ct)
; #pragma unroll
;         for (int tt = 0; tt < 4; ++tt) acc[ct][tt] = __builtin_amdgcn_mfma_f32_32x32x16_bf16(wf[ct], xf[tt], acc[ct][tt], 0, 0, 0);
;     }
	global_load_dwordx4 v[160:163], v[144:145], off offset:1280
	global_load_dwordx4 v[164:167], v[142:143], off offset:1280
	global_load_dwordx4 v[168:171], v[138:139], off offset:1280
	global_load_dwordx4 v[172:175], v[136:137], off offset:1280
	global_load_dwordx4 v[176:179], v[140:141], off offset:1280
	global_load_dwordx4 v[180:183], v[130:131], off offset:1280
	global_load_dwordx4 v[184:187], v[134:135], off offset:1280
	global_load_dwordx4 v[188:191], v[132:133], off offset:1280
	s_waitcnt vmcnt(8)
	ds_write_b128 v149, v[228:231] offset:36864
	ds_write_b128 v152, v[212:215] offset:36864
	ds_write_b128 v149, v[224:227] offset:46080
	ds_write_b128 v152, v[208:211] offset:46080
	ds_write_b128 v149, v[204:207] offset:55296
	ds_write_b128 v152, v[196:199] offset:55296
	ds_write_b128 v149, v[200:203] offset:64512
	ds_write_b128 v152, v[192:195] offset:64512
	ds_read_b128 v[192:195], v148
	ds_read_b128 v[196:199], v147
	ds_read_b128 v[200:203], v148 offset:32
	ds_read_b128 v[204:207], v147 offset:32
	ds_read_b128 v[208:211], v147 offset:4608
	ds_read_b128 v[212:215], v147 offset:4640
	ds_read_b128 v[224:227], v147 offset:9216
	ds_read_b128 v[228:231], v147 offset:9248
	ds_read_b128 v[232:235], v147 offset:13824
	ds_read_b128 v[236:239], v147 offset:13856
	s_waitcnt lgkmcnt(8)
	v_mfma_f32_32x32x16_bf16 v[98:113], v[192:195], v[196:199], v[98:113]
	s_waitcnt lgkmcnt(5)
	v_mfma_f32_32x32x16_bf16 v[82:97], v[192:195], v[208:211], v[82:97]
	s_waitcnt lgkmcnt(3)
	v_mfma_f32_32x32x16_bf16 v[50:65], v[192:195], v[224:227], v[50:65]
	s_waitcnt lgkmcnt(1)
	v_mfma_f32_32x32x16_bf16 v[18:33], v[192:195], v[232:235], v[18:33]
	ds_read_b128 v[192:195], v148 offset:4608
	ds_read_b128 v[240:243], v148 offset:4640
	s_waitcnt lgkmcnt(1)
	v_mfma_f32_32x32x16_bf16 v[114:129], v[192:195], v[196:199], v[114:129]
	v_mfma_f32_32x32x16_bf16 v[66:81], v[192:195], v[208:211], v[66:81]
	v_mfma_f32_32x32x16_bf16 v[34:49], v[192:195], v[224:227], v[34:49]
	v_mfma_f32_32x32x16_bf16 v[2:17], v[192:195], v[232:235], v[2:17]
	v_mfma_f32_32x32x16_bf16 v[98:113], v[200:203], v[204:207], v[98:113]
	v_mfma_f32_32x32x16_bf16 v[82:97], v[200:203], v[212:215], v[82:97]
	v_mfma_f32_32x32x16_bf16 v[50:65], v[200:203], v[228:231], v[50:65]
	v_mfma_f32_32x32x16_bf16 v[18:33], v[200:203], v[236:239], v[18:33]
	s_waitcnt lgkmcnt(0)
	v_mfma_f32_32x32x16_bf16 v[114:129], v[240:243], v[204:207], v[114:129]
	ds_read_b128 v[192:195], v148 offset:64
	ds_read_b128 v[196:199], v147 offset:64
	ds_read_b128 v[200:203], v148 offset:96
	ds_read_b128 v[204:207], v147 offset:96
	v_mfma_f32_32x32x16_bf16 v[66:81], v[240:243], v[212:215], v[66:81]
	ds_read_b128 v[208:211], v147 offset:4672
	ds_read_b128 v[212:215], v147 offset:4704
	v_mfma_f32_32x32x16_bf16 v[34:49], v[240:243], v[228:231], v[34:49]
	ds_read_b128 v[224:227], v147 offset:9280
	ds_read_b128 v[228:231], v147 offset:9312
	v_mfma_f32_32x32x16_bf16 v[2:17], v[240:243], v[236:239], v[2:17]
	ds_read_b128 v[232:235], v147 offset:13888
	ds_read_b128 v[236:239], v147 offset:13920
	s_waitcnt lgkmcnt(8)
	v_mfma_f32_32x32x16_bf16 v[98:113], v[192:195], v[196:199], v[98:113]
	s_waitcnt lgkmcnt(5)
	v_mfma_f32_32x32x16_bf16 v[82:97], v[192:195], v[208:211], v[82:97]
	s_waitcnt lgkmcnt(3)
	v_mfma_f32_32x32x16_bf16 v[50:65], v[192:195], v[224:227], v[50:65]
	s_waitcnt lgkmcnt(1)
	v_mfma_f32_32x32x16_bf16 v[18:33], v[192:195], v[232:235], v[18:33]
	ds_read_b128 v[192:195], v148 offset:4672
	ds_read_b128 v[240:243], v148 offset:4704
	s_waitcnt lgkmcnt(1)
	v_mfma_f32_32x32x16_bf16 v[114:129], v[192:195], v[196:199], v[114:129]
	v_mfma_f32_32x32x16_bf16 v[66:81], v[192:195], v[208:211], v[66:81]
	v_mfma_f32_32x32x16_bf16 v[34:49], v[192:195], v[224:227], v[34:49]
	v_mfma_f32_32x32x16_bf16 v[2:17], v[192:195], v[232:235], v[2:17]
	v_mfma_f32_32x32x16_bf16 v[98:113], v[200:203], v[204:207], v[98:113]
	v_mfma_f32_32x32x16_bf16 v[82:97], v[200:203], v[212:215], v[82:97]
	v_mfma_f32_32x32x16_bf16 v[50:65], v[200:203], v[228:231], v[50:65]
	v_mfma_f32_32x32x16_bf16 v[18:33], v[200:203], v[236:239], v[18:33]
	s_waitcnt lgkmcnt(0)
	v_mfma_f32_32x32x16_bf16 v[114:129], v[240:243], v[204:207], v[114:129]
	v_mfma_f32_32x32x16_bf16 v[66:81], v[240:243], v[212:215], v[66:81]
	v_mfma_f32_32x32x16_bf16 v[34:49], v[240:243], v[228:231], v[34:49]
	v_mfma_f32_32x32x16_bf16 v[2:17], v[240:243], v[236:239], v[2:17]
	s_barrier
;     ...
;   for (int kt = 0; kt < nk; ++kt) {
;     __syncthreads();
;     if (kt + 1 < nk) {
;       u16* aw = As0 + ((kt + 1) & 1) * 256 * LD;
;       u16* bw = Bs0 + ((kt + 1) & 1) * 256 * LD;
; #pragma unroll
;       for (int i = 0; i < 4; ++i) { *(u32x4*)(aw + (srow + 64 * i) * LD + skc * 8) = ra[i]; *(u32x4*)(bw + (srow + 64 * i) * LD + skc * 8) = rb[i]; }
;     }
;     if (kt + 2 < nk) {
; #pragma unroll
;       for (int i = 0; i < 4; ++i) { ra[i] = *(const u32x4*)(Ag + (size_t)(64 * i) * K + (kt + 2) * 64); rb[i] = *(const u32x4*)(Bg[i] + (kt + 2) * 64); }
;     }
;     __builtin_amdgcn_sched_barrier(0);
;     const u16* as = As0 + (kt & 1) * 256 * LD + (wr * 128 + l31) * LD + h * 8;
;     const u16* bs = Bs0 + (kt & 1) * 256 * LD + (wc * 64 + l31) * LD + h * 8;
;     if (domma)
; #pragma unroll
;     for (int ks = 0; ks < 4; ++ks) {
;       bf16x8 wf[2], xf[4];
; #pragma unroll
;       for (int ct = 0; ct < 2; ++ct) wf[ct] = *(const bf16x8*)(bs + ct * 32 * LD + ks * 16);
; #pragma unroll
;       for (int tt = 0; tt < 4; ++tt) xf[tt] = *(const bf16x8*)(as + tt * 32 * LD + ks * 16);
; #pragma unroll
;       for (int ct = 0; ct < 2; ++ct)
; #pragma unroll
;         for (int tt = 0; tt < 4; ++tt) acc[ct][tt] = __builtin_amdgcn_mfma_f32_32x32x16_bf16(wf[ct], xf[tt], acc[ct][tt], 0, 0, 0);
;     }
	global_load_dwordx4 v[192:195], v[144:145], off offset:1408
	global_load_dwordx4 v[196:199], v[142:143], off offset:1408
	global_load_dwordx4 v[200:203], v[138:139], off offset:1408
	global_load_dwordx4 v[204:207], v[136:137], off offset:1408
	global_load_dwordx4 v[208:211], v[140:141], off offset:1408
	global_load_dwordx4 v[212:215], v[130:131], off offset:1408
	global_load_dwordx4 v[224:227], v[134:135], off offset:1408
	global_load_dwordx4 v[228:231], v[132:133], off offset:1408
	s_waitcnt vmcnt(8)
	ds_write_b128 v149, v[188:191]
	ds_write_b128 v152, v[180:183]
	ds_write_b128 v149, v[184:187] offset:9216
	ds_write_b128 v152, v[176:179] offset:9216
	ds_write_b128 v149, v[172:175] offset:18432
	ds_write_b128 v152, v[164:167] offset:18432
	ds_write_b128 v149, v[168:171] offset:27648
	ds_write_b128 v152, v[160:163] offset:27648
	ds_read_b128 v[160:163], v148 offset:36864
	ds_read_b128 v[164:167], v147 offset:36864
	ds_read_b128 v[168:171], v148 offset:36896
	ds_read_b128 v[172:175], v147 offset:36896
	ds_read_b128 v[176:179], v147 offset:41472
	ds_read_b128 v[180:183], v147 offset:41504
	ds_read_b128 v[184:187], v147 offset:46080
	ds_read_b128 v[188:191], v147 offset:46112
	ds_read_b128 v[232:235], v147 offset:50688
	ds_read_b128 v[236:239], v147 offset:50720
	s_waitcnt lgkmcnt(8)
	v_mfma_f32_32x32x16_bf16 v[98:113], v[160:163], v[164:167], v[98:113]
	s_waitcnt lgkmcnt(5)
	v_mfma_f32_32x32x16_bf16 v[82:97], v[160:163], v[176:179], v[82:97]
	s_waitcnt lgkmcnt(3)
	v_mfma_f32_32x32x16_bf16 v[50:65], v[160:163], v[184:187], v[50:65]
	s_waitcnt lgkmcnt(1)
	v_mfma_f32_32x32x16_bf16 v[18:33], v[160:163], v[232:235], v[18:33]
	ds_read_b128 v[160:163], v148 offset:41472
	ds_read_b128 v[240:243], v148 offset:41504
	s_waitcnt lgkmcnt(1)
	v_mfma_f32_32x32x16_bf16 v[114:129], v[160:163], v[164:167], v[114:129]
	v_mfma_f32_32x32x16_bf16 v[66:81], v[160:163], v[176:179], v[66:81]
	v_mfma_f32_32x32x16_bf16 v[34:49], v[160:163], v[184:187], v[34:49]
	v_mfma_f32_32x32x16_bf16 v[2:17], v[160:163], v[232:235], v[2:17]
	v_mfma_f32_32x32x16_bf16 v[98:113], v[168:171], v[172:175], v[98:113]
	v_mfma_f32_32x32x16_bf16 v[82:97], v[168:171], v[180:183], v[82:97]
	v_mfma_f32_32x32x16_bf16 v[50:65], v[168:171], v[188:191], v[50:65]
	v_mfma_f32_32x32x16_bf16 v[18:33], v[168:171], v[236:239], v[18:33]
	s_waitcnt lgkmcnt(0)
	v_mfma_f32_32x32x16_bf16 v[114:129], v[240:243], v[172:175], v[114:129]
	ds_read_b128 v[160:163], v148 offset:36928
	ds_read_b128 v[164:167], v147 offset:36928
	ds_read_b128 v[168:171], v148 offset:36960
	ds_read_b128 v[172:175], v147 offset:36960
	v_mfma_f32_32x32x16_bf16 v[66:81], v[240:243], v[180:183], v[66:81]
	ds_read_b128 v[176:179], v147 offset:41536
	ds_read_b128 v[180:183], v147 offset:41568
	v_mfma_f32_32x32x16_bf16 v[34:49], v[240:243], v[188:191], v[34:49]
	ds_read_b128 v[184:187], v147 offset:46144
	ds_read_b128 v[188:191], v147 offset:46176
	v_mfma_f32_32x32x16_bf16 v[2:17], v[240:243], v[236:239], v[2:17]
	ds_read_b128 v[232:235], v147 offset:50752
	ds_read_b128 v[236:239], v147 offset:50784
	s_waitcnt lgkmcnt(8)
	v_mfma_f32_32x32x16_bf16 v[98:113], v[160:163], v[164:167], v[98:113]
	s_waitcnt lgkmcnt(5)
	v_mfma_f32_32x32x16_bf16 v[82:97], v[160:163], v[176:179], v[82:97]
	s_waitcnt lgkmcnt(3)
	v_mfma_f32_32x32x16_bf16 v[50:65], v[160:163], v[184:187], v[50:65]
	s_waitcnt lgkmcnt(1)
	v_mfma_f32_32x32x16_bf16 v[18:33], v[160:163], v[232:235], v[18:33]
	ds_read_b128 v[160:163], v148 offset:41536
	ds_read_b128 v[240:243], v148 offset:41568
	s_waitcnt lgkmcnt(1)
	v_mfma_f32_32x32x16_bf16 v[114:129], v[160:163], v[164:167], v[114:129]
	v_mfma_f32_32x32x16_bf16 v[66:81], v[160:163], v[176:179], v[66:81]
	v_mfma_f32_32x32x16_bf16 v[34:49], v[160:163], v[184:187], v[34:49]
	v_mfma_f32_32x32x16_bf16 v[2:17], v[160:163], v[232:235], v[2:17]
	v_mfma_f32_32x32x16_bf16 v[98:113], v[168:171], v[172:175], v[98:113]
	v_mfma_f32_32x32x16_bf16 v[82:97], v[168:171], v[180:183], v[82:97]
	v_mfma_f32_32x32x16_bf16 v[50:65], v[168:171], v[188:191], v[50:65]
	v_mfma_f32_32x32x16_bf16 v[18:33], v[168:171], v[236:239], v[18:33]
	s_waitcnt lgkmcnt(0)
	v_mfma_f32_32x32x16_bf16 v[114:129], v[240:243], v[172:175], v[114:129]
	v_mfma_f32_32x32x16_bf16 v[66:81], v[240:243], v[180:183], v[66:81]
	v_mfma_f32_32x32x16_bf16 v[34:49], v[240:243], v[188:191], v[34:49]
	v_mfma_f32_32x32x16_bf16 v[2:17], v[240:243], v[236:239], v[2:17]
	s_barrier
;     ...
;   for (int kt = 0; kt < nk; ++kt) {
;     __syncthreads();
;     if (kt + 1 < nk) {
;       u16* aw = As0 + ((kt + 1) & 1) * 256 * LD;
;       u16* bw = Bs0 + ((kt + 1) & 1) * 256 * LD;
; #pragma unroll
;       for (int i = 0; i < 4; ++i) { *(u32x4*)(aw + (srow + 64 * i) * LD + skc * 8) = ra[i]; *(u32x4*)(bw + (srow + 64 * i) * LD + skc * 8) = rb[i]; }
;     }
;     if (kt + 2 < nk) {
; #pragma unroll
;       for (int i = 0; i < 4; ++i) { ra[i] = *(const u32x4*)(Ag + (size_t)(64 * i) * K + (kt + 2) * 64); rb[i] = *(const u32x4*)(Bg[i] + (kt + 2) * 64); }
;     }
;     __builtin_amdgcn_sched_barrier(0);
;     const u16* as = As0 + (kt & 1) * 256 * LD + (wr * 128 + l31) * LD + h * 8;
;     const u16* bs = Bs0 + (kt & 1) * 256 * LD + (wc * 64 + l31) * LD + h * 8;
;     if (domma)
; #pragma unroll
;     for (int ks = 0; ks < 4; ++ks) {
;       bf16x8 wf[2], xf[4];
; #pragma unroll
;       for (int ct = 0; ct < 2; ++ct) wf[ct] = *(const bf16x8*)(bs + ct * 32 * LD + ks * 16);
; #pragma unroll
;       for (int tt = 0; tt < 4; ++tt) xf[tt] = *(const bf16x8*)(as + tt * 32 * LD + ks * 16);
; #pragma unroll
;       for (int ct = 0; ct < 2; ++ct)
; #pragma unroll
;         for (int tt = 0; tt < 4; ++tt) acc[ct][tt] = __builtin_amdgcn_mfma_f32_32x32x16_bf16(wf[ct], xf[tt], acc[ct][tt], 0, 0, 0);
;     }
	global_load_dwordx4 v[160:163], v[144:145], off offset:1536
	global_load_dwordx4 v[164:167], v[142:143], off offset:1536
	global_load_dwordx4 v[168:171], v[138:139], off offset:1536
	global_load_dwordx4 v[172:175], v[136:137], off offset:1536
	global_load_dwordx4 v[176:179], v[140:141], off offset:1536
	global_load_dwordx4 v[180:183], v[130:131], off offset:1536
	global_load_dwordx4 v[184:187], v[134:135], off offset:1536
	global_load_dwordx4 v[188:191], v[132:133], off offset:1536
	s_waitcnt vmcnt(8)
	ds_write_b128 v149, v[228:231] offset:36864
	ds_write_b128 v152, v[212:215] offset:36864
	ds_write_b128 v149, v[224:227] offset:46080
	ds_write_b128 v152, v[208:211] offset:46080
	ds_write_b128 v149, v[204:207] offset:55296
	ds_write_b128 v152, v[196:199] offset:55296
	ds_write_b128 v149, v[200:203] offset:64512
	ds_write_b128 v152, v[192:195] offset:64512
	ds_read_b128 v[192:195], v148
	ds_read_b128 v[196:199], v147
	ds_read_b128 v[200:203], v148 offset:32
	ds_read_b128 v[204:207], v147 offset:32
	ds_read_b128 v[208:211], v147 offset:4608
	ds_read_b128 v[212:215], v147 offset:4640
	ds_read_b128 v[224:227], v147 offset:9216
	ds_read_b128 v[228:231], v147 offset:9248
	ds_read_b128 v[232:235], v147 offset:13824
	ds_read_b128 v[236:239], v147 offset:13856
	s_waitcnt lgkmcnt(8)
	v_mfma_f32_32x32x16_bf16 v[98:113], v[192:195], v[196:199], v[98:113]
	s_waitcnt lgkmcnt(5)
	v_mfma_f32_32x32x16_bf16 v[82:97], v[192:195], v[208:211], v[82:97]
	s_waitcnt lgkmcnt(3)
	v_mfma_f32_32x32x16_bf16 v[50:65], v[192:195], v[224:227], v[50:65]
	s_waitcnt lgkmcnt(1)
	v_mfma_f32_32x32x16_bf16 v[18:33], v[192:195], v[232:235], v[18:33]
	ds_read_b128 v[192:195], v148 offset:4608
	ds_read_b128 v[240:243], v148 offset:4640
	s_waitcnt lgkmcnt(1)
	v_mfma_f32_32x32x16_bf16 v[114:129], v[192:195], v[196:199], v[114:129]
	v_mfma_f32_32x32x16_bf16 v[66:81], v[192:195], v[208:211], v[66:81]
	v_mfma_f32_32x32x16_bf16 v[34:49], v[192:195], v[224:227], v[34:49]
	v_mfma_f32_32x32x16_bf16 v[2:17], v[192:195], v[232:235], v[2:17]
	v_mfma_f32_32x32x16_bf16 v[98:113], v[200:203], v[204:207], v[98:113]
	v_mfma_f32_32x32x16_bf16 v[82:97], v[200:203], v[212:215], v[82:97]
	v_mfma_f32_32x32x16_bf16 v[50:65], v[200:203], v[228:231], v[50:65]
	v_mfma_f32_32x32x16_bf16 v[18:33], v[200:203], v[236:239], v[18:33]
	s_waitcnt lgkmcnt(0)
	v_mfma_f32_32x32x16_bf16 v[114:129], v[240:243], v[204:207], v[114:129]
	ds_read_b128 v[192:195], v148 offset:64
	ds_read_b128 v[196:199], v147 offset:64
	ds_read_b128 v[200:203], v148 offset:96
	ds_read_b128 v[204:207], v147 offset:96
	v_mfma_f32_32x32x16_bf16 v[66:81], v[240:243], v[212:215], v[66:81]
	ds_read_b128 v[208:211], v147 offset:4672
	ds_read_b128 v[212:215], v147 offset:4704
	v_mfma_f32_32x32x16_bf16 v[34:49], v[240:243], v[228:231], v[34:49]
	ds_read_b128 v[224:227], v147 offset:9280
	ds_read_b128 v[228:231], v147 offset:9312
	v_mfma_f32_32x32x16_bf16 v[2:17], v[240:243], v[236:239], v[2:17]
	ds_read_b128 v[232:235], v147 offset:13888
	ds_read_b128 v[236:239], v147 offset:13920
	s_waitcnt lgkmcnt(8)
	v_mfma_f32_32x32x16_bf16 v[98:113], v[192:195], v[196:199], v[98:113]
	s_waitcnt lgkmcnt(5)
	v_mfma_f32_32x32x16_bf16 v[82:97], v[192:195], v[208:211], v[82:97]
	s_waitcnt lgkmcnt(3)
	v_mfma_f32_32x32x16_bf16 v[50:65], v[192:195], v[224:227], v[50:65]
	s_waitcnt lgkmcnt(1)
	v_mfma_f32_32x32x16_bf16 v[18:33], v[192:195], v[232:235], v[18:33]
	ds_read_b128 v[192:195], v148 offset:4672
	ds_read_b128 v[240:243], v148 offset:4704
	s_waitcnt lgkmcnt(1)
	v_mfma_f32_32x32x16_bf16 v[114:129], v[192:195], v[196:199], v[114:129]
	v_mfma_f32_32x32x16_bf16 v[66:81], v[192:195], v[208:211], v[66:81]
	v_mfma_f32_32x32x16_bf16 v[34:49], v[192:195], v[224:227], v[34:49]
	v_mfma_f32_32x32x16_bf16 v[2:17], v[192:195], v[232:235], v[2:17]
	v_mfma_f32_32x32x16_bf16 v[98:113], v[200:203], v[204:207], v[98:113]
	v_mfma_f32_32x32x16_bf16 v[82:97], v[200:203], v[212:215], v[82:97]
	v_mfma_f32_32x32x16_bf16 v[50:65], v[200:203], v[228:231], v[50:65]
	v_mfma_f32_32x32x16_bf16 v[18:33], v[200:203], v[236:239], v[18:33]
	s_waitcnt lgkmcnt(0)
	v_mfma_f32_32x32x16_bf16 v[114:129], v[240:243], v[204:207], v[114:129]
	v_mfma_f32_32x32x16_bf16 v[66:81], v[240:243], v[212:215], v[66:81]
	v_mfma_f32_32x32x16_bf16 v[34:49], v[240:243], v[228:231], v[34:49]
	v_mfma_f32_32x32x16_bf16 v[2:17], v[240:243], v[236:239], v[2:17]
	s_barrier
;     ...
;   for (int kt = 0; kt < nk; ++kt) {
;     __syncthreads();
;     if (kt + 1 < nk) {
;       u16* aw = As0 + ((kt + 1) & 1) * 256 * LD;
;       u16* bw = Bs0 + ((kt + 1) & 1) * 256 * LD;
; #pragma unroll
;       for (int i = 0; i < 4; ++i) { *(u32x4*)(aw + (srow + 64 * i) * LD + skc * 8) = ra[i]; *(u32x4*)(bw + (srow + 64 * i) * LD + skc * 8) = rb[i]; }
;     }
;     if (kt + 2 < nk) {
; #pragma unroll
;       for (int i = 0; i < 4; ++i) { ra[i] = *(const u32x4*)(Ag + (size_t)(64 * i) * K + (kt + 2) * 64); rb[i] = *(const u32x4*)(Bg[i] + (kt + 2) * 64); }
;     }
;     __builtin_amdgcn_sched_barrier(0);
;     const u16* as = As0 + (kt & 1) * 256 * LD + (wr * 128 + l31) * LD + h * 8;
;     const u16* bs = Bs0 + (kt & 1) * 256 * LD + (wc * 64 + l31) * LD + h * 8;
;     if (domma)
; #pragma unroll
;     for (int ks = 0; ks < 4; ++ks) {
;       bf16x8 wf[2], xf[4];
; #pragma unroll
;       for (int ct = 0; ct < 2; ++ct) wf[ct] = *(const bf16x8*)(bs + ct * 32 * LD + ks * 16);
; #pragma unroll
;       for (int tt = 0; tt < 4; ++tt) xf[tt] = *(const bf16x8*)(as + tt * 32 * LD + ks * 16);
; #pragma unroll
;       for (int ct = 0; ct < 2; ++ct)
; #pragma unroll
;         for (int tt = 0; tt < 4; ++tt) acc[ct][tt] = __builtin_amdgcn_mfma_f32_32x32x16_bf16(wf[ct], xf[tt], acc[ct][tt], 0, 0, 0);
;     }
	global_load_dwordx4 v[192:195], v[144:145], off offset:1664
	global_load_dwordx4 v[196:199], v[142:143], off offset:1664
	global_load_dwordx4 v[200:203], v[138:139], off offset:1664
	global_load_dwordx4 v[204:207], v[136:137], off offset:1664
	global_load_dwordx4 v[208:211], v[140:141], off offset:1664
	global_load_dwordx4 v[212:215], v[130:131], off offset:1664
	global_load_dwordx4 v[224:227], v[134:135], off offset:1664
	global_load_dwordx4 v[228:231], v[132:133], off offset:1664
	s_waitcnt vmcnt(8)
	ds_write_b128 v149, v[188:191]
	ds_write_b128 v152, v[180:183]
	ds_write_b128 v149, v[184:187] offset:9216
	ds_write_b128 v152, v[176:179] offset:9216
	ds_write_b128 v149, v[172:175] offset:18432
	ds_write_b128 v152, v[164:167] offset:18432
	ds_write_b128 v149, v[168:171] offset:27648
	ds_write_b128 v152, v[160:163] offset:27648
	ds_read_b128 v[160:163], v148 offset:36864
	ds_read_b128 v[164:167], v147 offset:36864
	ds_read_b128 v[168:171], v148 offset:36896
	ds_read_b128 v[172:175], v147 offset:36896
	ds_read_b128 v[176:179], v147 offset:41472
	ds_read_b128 v[180:183], v147 offset:41504
	ds_read_b128 v[184:187], v147 offset:46080
	ds_read_b128 v[188:191], v147 offset:46112
	ds_read_b128 v[232:235], v147 offset:50688
	ds_read_b128 v[236:239], v147 offset:50720
	s_waitcnt lgkmcnt(8)
	v_mfma_f32_32x32x16_bf16 v[98:113], v[160:163], v[164:167], v[98:113]
	s_waitcnt lgkmcnt(5)
	v_mfma_f32_32x32x16_bf16 v[82:97], v[160:163], v[176:179], v[82:97]
	s_waitcnt lgkmcnt(3)
	v_mfma_f32_32x32x16_bf16 v[50:65], v[160:163], v[184:187], v[50:65]
	s_waitcnt lgkmcnt(1)
	v_mfma_f32_32x32x16_bf16 v[18:33], v[160:163], v[232:235], v[18:33]
	ds_read_b128 v[160:163], v148 offset:41472
	ds_read_b128 v[240:243], v148 offset:41504
	s_waitcnt lgkmcnt(1)
	v_mfma_f32_32x32x16_bf16 v[114:129], v[160:163], v[164:167], v[114:129]
	v_mfma_f32_32x32x16_bf16 v[66:81], v[160:163], v[176:179], v[66:81]
	v_mfma_f32_32x32x16_bf16 v[34:49], v[160:163], v[184:187], v[34:49]
	v_mfma_f32_32x32x16_bf16 v[2:17], v[160:163], v[232:235], v[2:17]
	v_mfma_f32_32x32x16_bf16 v[98:113], v[168:171], v[172:175], v[98:113]
	v_mfma_f32_32x32x16_bf16 v[82:97], v[168:171], v[180:183], v[82:97]
	v_mfma_f32_32x32x16_bf16 v[50:65], v[168:171], v[188:191], v[50:65]
	v_mfma_f32_32x32x16_bf16 v[18:33], v[168:171], v[236:239], v[18:33]
	s_waitcnt lgkmcnt(0)
	v_mfma_f32_32x32x16_bf16 v[114:129], v[240:243], v[172:175], v[114:129]
	ds_read_b128 v[160:163], v148 offset:36928
	ds_read_b128 v[164:167], v147 offset:36928
	ds_read_b128 v[168:171], v148 offset:36960
	ds_read_b128 v[172:175], v147 offset:36960
	v_mfma_f32_32x32x16_bf16 v[66:81], v[240:243], v[180:183], v[66:81]
	ds_read_b128 v[176:179], v147 offset:41536
	ds_read_b128 v[180:183], v147 offset:41568
	v_mfma_f32_32x32x16_bf16 v[34:49], v[240:243], v[188:191], v[34:49]
	ds_read_b128 v[184:187], v147 offset:46144
	ds_read_b128 v[188:191], v147 offset:46176
	v_mfma_f32_32x32x16_bf16 v[2:17], v[240:243], v[236:239], v[2:17]
	ds_read_b128 v[232:235], v147 offset:50752
	ds_read_b128 v[236:239], v147 offset:50784
	s_waitcnt lgkmcnt(8)
	v_mfma_f32_32x32x16_bf16 v[98:113], v[160:163], v[164:167], v[98:113]
	s_waitcnt lgkmcnt(5)
	v_mfma_f32_32x32x16_bf16 v[82:97], v[160:163], v[176:179], v[82:97]
	s_waitcnt lgkmcnt(3)
	v_mfma_f32_32x32x16_bf16 v[50:65], v[160:163], v[184:187], v[50:65]
	s_waitcnt lgkmcnt(1)
	v_mfma_f32_32x32x16_bf16 v[18:33], v[160:163], v[232:235], v[18:33]
	ds_read_b128 v[160:163], v148 offset:41536
	ds_read_b128 v[240:243], v148 offset:41568
	s_waitcnt lgkmcnt(1)
	v_mfma_f32_32x32x16_bf16 v[114:129], v[160:163], v[164:167], v[114:129]
	v_mfma_f32_32x32x16_bf16 v[66:81], v[160:163], v[176:179], v[66:81]
	v_mfma_f32_32x32x16_bf16 v[34:49], v[160:163], v[184:187], v[34:49]
	v_mfma_f32_32x32x16_bf16 v[2:17], v[160:163], v[232:235], v[2:17]
	v_mfma_f32_32x32x16_bf16 v[98:113], v[168:171], v[172:175], v[98:113]
	v_mfma_f32_32x32x16_bf16 v[82:97], v[168:171], v[180:183], v[82:97]
	v_mfma_f32_32x32x16_bf16 v[50:65], v[168:171], v[188:191], v[50:65]
	v_mfma_f32_32x32x16_bf16 v[18:33], v[168:171], v[236:239], v[18:33]
	s_waitcnt lgkmcnt(0)
	v_mfma_f32_32x32x16_bf16 v[114:129], v[240:243], v[172:175], v[114:129]
	v_mfma_f32_32x32x16_bf16 v[66:81], v[240:243], v[180:183], v[66:81]
	v_mfma_f32_32x32x16_bf16 v[34:49], v[240:243], v[188:191], v[34:49]
	v_mfma_f32_32x32x16_bf16 v[2:17], v[240:243], v[236:239], v[2:17]
	s_barrier
;     ...
;   for (int kt = 0; kt < nk; ++kt) {
;     __syncthreads();
;     if (kt + 1 < nk) {
;       u16* aw = As0 + ((kt + 1) & 1) * 256 * LD;
;       u16* bw = Bs0 + ((kt + 1) & 1) * 256 * LD;
; #pragma unroll
;       for (int i = 0; i < 4; ++i) { *(u32x4*)(aw + (srow + 64 * i) * LD + skc * 8) = ra[i]; *(u32x4*)(bw + (srow + 64 * i) * LD + skc * 8) = rb[i]; }
;     }
;     if (kt + 2 < nk) {
; #pragma unroll
;       for (int i = 0; i < 4; ++i) { ra[i] = *(const u32x4*)(Ag + (size_t)(64 * i) * K + (kt + 2) * 64); rb[i] = *(const u32x4*)(Bg[i] + (kt + 2) * 64); }
;     }
;     __builtin_amdgcn_sched_barrier(0);
;     const u16* as = As0 + (kt & 1) * 256 * LD + (wr * 128 + l31) * LD + h * 8;
;     const u16* bs = Bs0 + (kt & 1) * 256 * LD + (wc * 64 + l31) * LD + h * 8;
;     if (domma)
; #pragma unroll
;     for (int ks = 0; ks < 4; ++ks) {
;       bf16x8 wf[2], xf[4];
; #pragma unroll
;       for (int ct = 0; ct < 2; ++ct) wf[ct] = *(const bf16x8*)(bs + ct * 32 * LD + ks * 16);
; #pragma unroll
;       for (int tt = 0; tt < 4; ++tt) xf[tt] = *(const bf16x8*)(as + tt * 32 * LD + ks * 16);
; #pragma unroll
;       for (int ct = 0; ct < 2; ++ct)
; #pragma unroll
;         for (int tt = 0; tt < 4; ++tt) acc[ct][tt] = __builtin_amdgcn_mfma_f32_32x32x16_bf16(wf[ct], xf[tt], acc[ct][tt], 0, 0, 0);
;     }
	global_load_dwordx4 v[160:163], v[144:145], off offset:1792
	global_load_dwordx4 v[164:167], v[142:143], off offset:1792
	global_load_dwordx4 v[168:171], v[138:139], off offset:1792
	global_load_dwordx4 v[172:175], v[136:137], off offset:1792
	global_load_dwordx4 v[176:179], v[140:141], off offset:1792
	global_load_dwordx4 v[180:183], v[130:131], off offset:1792
	global_load_dwordx4 v[184:187], v[134:135], off offset:1792
	global_load_dwordx4 v[188:191], v[132:133], off offset:1792
	s_waitcnt vmcnt(8)
	ds_write_b128 v149, v[228:231] offset:36864
	ds_write_b128 v152, v[212:215] offset:36864
	ds_write_b128 v149, v[224:227] offset:46080
	ds_write_b128 v152, v[208:211] offset:46080
	ds_write_b128 v149, v[204:207] offset:55296
	ds_write_b128 v152, v[196:199] offset:55296
	ds_write_b128 v149, v[200:203] offset:64512
	ds_write_b128 v152, v[192:195] offset:64512
	ds_read_b128 v[192:195], v148
	ds_read_b128 v[196:199], v147
	ds_read_b128 v[200:203], v148 offset:32
	ds_read_b128 v[204:207], v147 offset:32
	ds_read_b128 v[208:211], v147 offset:4608
	ds_read_b128 v[212:215], v147 offset:4640
	ds_read_b128 v[224:227], v147 offset:9216
	ds_read_b128 v[228:231], v147 offset:9248
	ds_read_b128 v[232:235], v147 offset:13824
	ds_read_b128 v[236:239], v147 offset:13856
	s_waitcnt lgkmcnt(8)
	v_mfma_f32_32x32x16_bf16 v[98:113], v[192:195], v[196:199], v[98:113]
	s_waitcnt lgkmcnt(5)
	v_mfma_f32_32x32x16_bf16 v[82:97], v[192:195], v[208:211], v[82:97]
	s_waitcnt lgkmcnt(3)
	v_mfma_f32_32x32x16_bf16 v[50:65], v[192:195], v[224:227], v[50:65]
	s_waitcnt lgkmcnt(1)
	v_mfma_f32_32x32x16_bf16 v[18:33], v[192:195], v[232:235], v[18:33]
	ds_read_b128 v[192:195], v148 offset:4608
	ds_read_b128 v[240:243], v148 offset:4640
	s_waitcnt lgkmcnt(1)
	v_mfma_f32_32x32x16_bf16 v[114:129], v[192:195], v[196:199], v[114:129]
	v_mfma_f32_32x32x16_bf16 v[66:81], v[192:195], v[208:211], v[66:81]
	v_mfma_f32_32x32x16_bf16 v[34:49], v[192:195], v[224:227], v[34:49]
	v_mfma_f32_32x32x16_bf16 v[2:17], v[192:195], v[232:235], v[2:17]
	v_mfma_f32_32x32x16_bf16 v[98:113], v[200:203], v[204:207], v[98:113]
	v_mfma_f32_32x32x16_bf16 v[82:97], v[200:203], v[212:215], v[82:97]
	v_mfma_f32_32x32x16_bf16 v[50:65], v[200:203], v[228:231], v[50:65]
	v_mfma_f32_32x32x16_bf16 v[18:33], v[200:203], v[236:239], v[18:33]
	s_waitcnt lgkmcnt(0)
	v_mfma_f32_32x32x16_bf16 v[114:129], v[240:243], v[204:207], v[114:129]
	ds_read_b128 v[192:195], v148 offset:64
	ds_read_b128 v[196:199], v147 offset:64
	ds_read_b128 v[200:203], v148 offset:96
	ds_read_b128 v[204:207], v147 offset:96
	v_mfma_f32_32x32x16_bf16 v[66:81], v[240:243], v[212:215], v[66:81]
	ds_read_b128 v[208:211], v147 offset:4672
	ds_read_b128 v[212:215], v147 offset:4704
	v_mfma_f32_32x32x16_bf16 v[34:49], v[240:243], v[228:231], v[34:49]
	ds_read_b128 v[224:227], v147 offset:9280
	ds_read_b128 v[228:231], v147 offset:9312
	v_mfma_f32_32x32x16_bf16 v[2:17], v[240:243], v[236:239], v[2:17]
	ds_read_b128 v[232:235], v147 offset:13888
	ds_read_b128 v[236:239], v147 offset:13920
	s_waitcnt lgkmcnt(8)
	v_mfma_f32_32x32x16_bf16 v[98:113], v[192:195], v[196:199], v[98:113]
	s_waitcnt lgkmcnt(5)
	v_mfma_f32_32x32x16_bf16 v[82:97], v[192:195], v[208:211], v[82:97]
	s_waitcnt lgkmcnt(3)
	v_mfma_f32_32x32x16_bf16 v[50:65], v[192:195], v[224:227], v[50:65]
	s_waitcnt lgkmcnt(1)
	v_mfma_f32_32x32x16_bf16 v[18:33], v[192:195], v[232:235], v[18:33]
	ds_read_b128 v[192:195], v148 offset:4672
	ds_read_b128 v[240:243], v148 offset:4704
	s_waitcnt lgkmcnt(1)
	v_mfma_f32_32x32x16_bf16 v[114:129], v[192:195], v[196:199], v[114:129]
	v_mfma_f32_32x32x16_bf16 v[66:81], v[192:195], v[208:211], v[66:81]
	v_mfma_f32_32x32x16_bf16 v[34:49], v[192:195], v[224:227], v[34:49]
	v_mfma_f32_32x32x16_bf16 v[2:17], v[192:195], v[232:235], v[2:17]
	v_mfma_f32_32x32x16_bf16 v[98:113], v[200:203], v[204:207], v[98:113]
	v_mfma_f32_32x32x16_bf16 v[82:97], v[200:203], v[212:215], v[82:97]
	v_mfma_f32_32x32x16_bf16 v[50:65], v[200:203], v[228:231], v[50:65]
	v_mfma_f32_32x32x16_bf16 v[18:33], v[200:203], v[236:239], v[18:33]
	s_waitcnt lgkmcnt(0)
	v_mfma_f32_32x32x16_bf16 v[114:129], v[240:243], v[204:207], v[114:129]
	v_mfma_f32_32x32x16_bf16 v[66:81], v[240:243], v[212:215], v[66:81]
	v_mfma_f32_32x32x16_bf16 v[34:49], v[240:243], v[228:231], v[34:49]
	v_mfma_f32_32x32x16_bf16 v[2:17], v[240:243], v[236:239], v[2:17]
	s_barrier
;     ...
;   for (int kt = 0; kt < nk; ++kt) {
;     __syncthreads();
;     if (kt + 1 < nk) {
;       u16* aw = As0 + ((kt + 1) & 1) * 256 * LD;
;       u16* bw = Bs0 + ((kt + 1) & 1) * 256 * LD;
; #pragma unroll
;       for (int i = 0; i < 4; ++i) { *(u32x4*)(aw + (srow + 64 * i) * LD + skc * 8) = ra[i]; *(u32x4*)(bw + (srow + 64 * i) * LD + skc * 8) = rb[i]; }
;     }
;     if (kt + 2 < nk) {
; #pragma unroll
;       for (int i = 0; i < 4; ++i) { ra[i] = *(const u32x4*)(Ag + (size_t)(64 * i) * K + (kt + 2) * 64); rb[i] = *(const u32x4*)(Bg[i] + (kt + 2) * 64); }
;     }
;     __builtin_amdgcn_sched_barrier(0);
;     const u16* as = As0 + (kt & 1) * 256 * LD + (wr * 128 + l31) * LD + h * 8;
;     const u16* bs = Bs0 + (kt & 1) * 256 * LD + (wc * 64 + l31) * LD + h * 8;
;     if (domma)
; #pragma unroll
;     for (int ks = 0; ks < 4; ++ks) {
;       bf16x8 wf[2], xf[4];
; #pragma unroll
;       for (int ct = 0; ct < 2; ++ct) wf[ct] = *(const bf16x8*)(bs + ct * 32 * LD + ks * 16);
; #pragma unroll
;       for (int tt = 0; tt < 4; ++tt) xf[tt] = *(const bf16x8*)(as + tt * 32 * LD + ks * 16);
; #pragma unroll
;       for (int ct = 0; ct < 2; ++ct)
; #pragma unroll
;         for (int tt = 0; tt < 4; ++tt) acc[ct][tt] = __builtin_amdgcn_mfma_f32_32x32x16_bf16(wf[ct], xf[tt], acc[ct][tt], 0, 0, 0);
;     }
	global_load_dwordx4 v[192:195], v[144:145], off offset:1920
	s_nop 0
	global_load_dwordx4 v[142:145], v[142:143], off offset:1920
	s_nop 0
	global_load_dwordx4 v[196:199], v[138:139], off offset:1920
	s_nop 0
	global_load_dwordx4 v[136:139], v[136:137], off offset:1920
	s_nop 0
	global_load_dwordx4 v[200:203], v[140:141], off offset:1920
	global_load_dwordx4 v[204:207], v[130:131], off offset:1920
	global_load_dwordx4 v[208:211], v[134:135], off offset:1920
	s_nop 0
	global_load_dwordx4 v[130:133], v[132:133], off offset:1920
	s_waitcnt vmcnt(8)
	ds_write_b128 v149, v[188:191]
	ds_write_b128 v152, v[180:183]
	ds_write_b128 v149, v[184:187] offset:9216
	ds_write_b128 v152, v[176:179] offset:9216
	ds_write_b128 v149, v[172:175] offset:18432
	ds_write_b128 v152, v[164:167] offset:18432
	ds_write_b128 v149, v[168:171] offset:27648
	ds_write_b128 v152, v[160:163] offset:27648
	ds_read_b128 v[160:163], v148 offset:36864
	ds_read_b128 v[164:167], v147 offset:36864
	ds_read_b128 v[168:171], v148 offset:36896
	ds_read_b128 v[172:175], v147 offset:36896
	ds_read_b128 v[176:179], v147 offset:41472
	ds_read_b128 v[180:183], v147 offset:41504
	ds_read_b128 v[184:187], v147 offset:46080
	ds_read_b128 v[188:191], v147 offset:46112
	ds_read_b128 v[212:215], v147 offset:50688
	ds_read_b128 v[224:227], v147 offset:50720
	s_waitcnt lgkmcnt(8)
	v_mfma_f32_32x32x16_bf16 v[98:113], v[160:163], v[164:167], v[98:113]
	s_waitcnt lgkmcnt(5)
	v_mfma_f32_32x32x16_bf16 v[82:97], v[160:163], v[176:179], v[82:97]
	s_waitcnt lgkmcnt(3)
	v_mfma_f32_32x32x16_bf16 v[50:65], v[160:163], v[184:187], v[50:65]
	s_waitcnt lgkmcnt(1)
	v_mfma_f32_32x32x16_bf16 v[18:33], v[160:163], v[212:215], v[18:33]
	ds_read_b128 v[160:163], v148 offset:41472
	ds_read_b128 v[228:231], v148 offset:41504
	s_waitcnt lgkmcnt(1)
	v_mfma_f32_32x32x16_bf16 v[114:129], v[160:163], v[164:167], v[114:129]
	v_mfma_f32_32x32x16_bf16 v[66:81], v[160:163], v[176:179], v[66:81]
	v_mfma_f32_32x32x16_bf16 v[34:49], v[160:163], v[184:187], v[34:49]
	v_mfma_f32_32x32x16_bf16 v[2:17], v[160:163], v[212:215], v[2:17]
	v_mfma_f32_32x32x16_bf16 v[98:113], v[168:171], v[172:175], v[98:113]
	v_mfma_f32_32x32x16_bf16 v[82:97], v[168:171], v[180:183], v[82:97]
	v_mfma_f32_32x32x16_bf16 v[50:65], v[168:171], v[188:191], v[50:65]
	v_mfma_f32_32x32x16_bf16 v[18:33], v[168:171], v[224:227], v[18:33]
	s_waitcnt lgkmcnt(0)
	v_mfma_f32_32x32x16_bf16 v[114:129], v[228:231], v[172:175], v[114:129]
	ds_read_b128 v[160:163], v148 offset:36928
	ds_read_b128 v[164:167], v147 offset:36928
	ds_read_b128 v[168:171], v148 offset:36960
	ds_read_b128 v[172:175], v147 offset:36960
	v_mfma_f32_32x32x16_bf16 v[66:81], v[228:231], v[180:183], v[66:81]
	ds_read_b128 v[176:179], v147 offset:41536
	ds_read_b128 v[180:183], v147 offset:41568
	v_mfma_f32_32x32x16_bf16 v[34:49], v[228:231], v[188:191], v[34:49]
	ds_read_b128 v[184:187], v147 offset:46144
	ds_read_b128 v[188:191], v147 offset:46176
	v_mfma_f32_32x32x16_bf16 v[2:17], v[228:231], v[224:227], v[2:17]
	ds_read_b128 v[212:215], v147 offset:50752
	ds_read_b128 v[224:227], v147 offset:50784
	s_waitcnt lgkmcnt(8)
	v_mfma_f32_32x32x16_bf16 v[98:113], v[160:163], v[164:167], v[98:113]
	s_waitcnt lgkmcnt(5)
	v_mfma_f32_32x32x16_bf16 v[82:97], v[160:163], v[176:179], v[82:97]
	s_waitcnt lgkmcnt(3)
	v_mfma_f32_32x32x16_bf16 v[50:65], v[160:163], v[184:187], v[50:65]
	s_waitcnt lgkmcnt(1)
	v_mfma_f32_32x32x16_bf16 v[18:33], v[160:163], v[212:215], v[18:33]
	ds_read_b128 v[160:163], v148 offset:41536
	ds_read_b128 v[228:231], v148 offset:41568
	s_waitcnt lgkmcnt(1)
	v_mfma_f32_32x32x16_bf16 v[114:129], v[160:163], v[164:167], v[114:129]
	v_mfma_f32_32x32x16_bf16 v[66:81], v[160:163], v[176:179], v[66:81]
	v_mfma_f32_32x32x16_bf16 v[34:49], v[160:163], v[184:187], v[34:49]
	v_mfma_f32_32x32x16_bf16 v[2:17], v[160:163], v[212:215], v[2:17]
	v_mfma_f32_32x32x16_bf16 v[98:113], v[168:171], v[172:175], v[98:113]
	v_mfma_f32_32x32x16_bf16 v[82:97], v[168:171], v[180:183], v[82:97]
	v_mfma_f32_32x32x16_bf16 v[50:65], v[168:171], v[188:191], v[50:65]
	v_mfma_f32_32x32x16_bf16 v[18:33], v[168:171], v[224:227], v[18:33]
	s_waitcnt lgkmcnt(0)
	v_mfma_f32_32x32x16_bf16 v[114:129], v[228:231], v[172:175], v[114:129]
	v_mfma_f32_32x32x16_bf16 v[66:81], v[228:231], v[180:183], v[66:81]
	v_mfma_f32_32x32x16_bf16 v[34:49], v[228:231], v[188:191], v[34:49]
	v_mfma_f32_32x32x16_bf16 v[2:17], v[228:231], v[224:227], v[2:17]
	s_barrier
;     ...
;   for (int kt = 0; kt < nk; ++kt) {
;     __syncthreads();
;     if (kt + 1 < nk) {
;       u16* aw = As0 + ((kt + 1) & 1) * 256 * LD;
;       u16* bw = Bs0 + ((kt + 1) & 1) * 256 * LD;
; #pragma unroll
;       for (int i = 0; i < 4; ++i) { *(u32x4*)(aw + (srow + 64 * i) * LD + skc * 8) = ra[i]; *(u32x4*)(bw + (srow + 64 * i) * LD + skc * 8) = rb[i]; }
;     }
;     if (kt + 2 < nk) {
; #pragma unroll
;       for (int i = 0; i < 4; ++i) { ra[i] = *(const u32x4*)(Ag + (size_t)(64 * i) * K + (kt + 2) * 64); rb[i] = *(const u32x4*)(Bg[i] + (kt + 2) * 64); }
;     }
;     __builtin_amdgcn_sched_barrier(0);
;     const u16* as = As0 + (kt & 1) * 256 * LD + (wr * 128 + l31) * LD + h * 8;
;     const u16* bs = Bs0 + (kt & 1) * 256 * LD + (wc * 64 + l31) * LD + h * 8;
;     if (domma)
; #pragma unroll
;     for (int ks = 0; ks < 4; ++ks) {
;       bf16x8 wf[2], xf[4];
; #pragma unroll
;       for (int ct = 0; ct < 2; ++ct) wf[ct] = *(const bf16x8*)(bs + ct * 32 * LD + ks * 16);
; #pragma unroll
;       for (int tt = 0; tt < 4; ++tt) xf[tt] = *(const bf16x8*)(as + tt * 32 * LD + ks * 16);
; #pragma unroll
;       for (int ct = 0; ct < 2; ++ct)
; #pragma unroll
;         for (int tt = 0; tt < 4; ++tt) acc[ct][tt] = __builtin_amdgcn_mfma_f32_32x32x16_bf16(wf[ct], xf[tt], acc[ct][tt], 0, 0, 0);
;     }
;     __builtin_amdgcn_sched_barrier(0);
;   }
;   __syncthreads();
	s_waitcnt vmcnt(0)
	ds_write_b128 v149, v[130:133] offset:36864
	ds_write_b128 v152, v[204:207] offset:36864
	ds_write_b128 v149, v[208:211] offset:46080
	ds_write_b128 v152, v[200:203] offset:46080
	ds_write_b128 v149, v[136:139] offset:55296
	ds_write_b128 v152, v[142:145] offset:55296
	ds_write_b128 v149, v[196:199] offset:64512
	ds_write_b128 v152, v[192:195] offset:64512
	ds_read_b128 v[130:133], v148
	ds_read_b128 v[134:137], v147
	ds_read_b128 v[138:141], v148 offset:32
	ds_read_b128 v[142:145], v147 offset:32
	ds_read_b128 v[152:155], v147 offset:4608
	ds_read_b128 v[160:163], v147 offset:4640
	ds_read_b128 v[164:167], v147 offset:9216
	ds_read_b128 v[168:171], v147 offset:9248
	ds_read_b128 v[172:175], v147 offset:13824
	ds_read_b128 v[176:179], v147 offset:13856
	s_waitcnt lgkmcnt(8)
	v_mfma_f32_32x32x16_bf16 v[98:113], v[130:133], v[134:137], v[98:113]
	s_waitcnt lgkmcnt(5)
	v_mfma_f32_32x32x16_bf16 v[82:97], v[130:133], v[152:155], v[82:97]
	s_waitcnt lgkmcnt(3)
	v_mfma_f32_32x32x16_bf16 v[50:65], v[130:133], v[164:167], v[50:65]
	s_waitcnt lgkmcnt(1)
	v_mfma_f32_32x32x16_bf16 v[18:33], v[130:133], v[172:175], v[18:33]
	ds_read_b128 v[130:133], v148 offset:4608
	ds_read_b128 v[180:183], v148 offset:4640
	s_waitcnt lgkmcnt(1)
	v_mfma_f32_32x32x16_bf16 v[114:129], v[130:133], v[134:137], v[114:129]
	v_mfma_f32_32x32x16_bf16 v[66:81], v[130:133], v[152:155], v[66:81]
	v_mfma_f32_32x32x16_bf16 v[34:49], v[130:133], v[164:167], v[34:49]
	v_mfma_f32_32x32x16_bf16 v[2:17], v[130:133], v[172:175], v[2:17]
	v_mfma_f32_32x32x16_bf16 v[98:113], v[138:141], v[142:145], v[98:113]
	v_mfma_f32_32x32x16_bf16 v[82:97], v[138:141], v[160:163], v[82:97]
	v_mfma_f32_32x32x16_bf16 v[50:65], v[138:141], v[168:171], v[50:65]
	v_mfma_f32_32x32x16_bf16 v[18:33], v[138:141], v[176:179], v[18:33]
	s_waitcnt lgkmcnt(0)
	v_mfma_f32_32x32x16_bf16 v[114:129], v[180:183], v[142:145], v[114:129]
	ds_read_b128 v[130:133], v148 offset:64
	ds_read_b128 v[134:137], v147 offset:64
	ds_read_b128 v[138:141], v148 offset:96
	ds_read_b128 v[142:145], v147 offset:96
	v_mfma_f32_32x32x16_bf16 v[66:81], v[180:183], v[160:163], v[66:81]
	ds_read_b128 v[152:155], v147 offset:4672
	ds_read_b128 v[160:163], v147 offset:4704
	v_mfma_f32_32x32x16_bf16 v[34:49], v[180:183], v[168:171], v[34:49]
	ds_read_b128 v[164:167], v147 offset:9280
	ds_read_b128 v[168:171], v147 offset:9312
	v_mfma_f32_32x32x16_bf16 v[2:17], v[180:183], v[176:179], v[2:17]
	ds_read_b128 v[172:175], v147 offset:13888
	ds_read_b128 v[176:179], v147 offset:13920
	s_waitcnt lgkmcnt(8)
	v_mfma_f32_32x32x16_bf16 v[98:113], v[130:133], v[134:137], v[98:113]
	s_waitcnt lgkmcnt(5)
	v_mfma_f32_32x32x16_bf16 v[82:97], v[130:133], v[152:155], v[82:97]
	s_waitcnt lgkmcnt(3)
	v_mfma_f32_32x32x16_bf16 v[50:65], v[130:133], v[164:167], v[50:65]
	s_waitcnt lgkmcnt(1)
	v_mfma_f32_32x32x16_bf16 v[18:33], v[130:133], v[172:175], v[18:33]
	ds_read_b128 v[130:133], v148 offset:4672
	ds_read_b128 v[180:183], v148 offset:4704
	s_waitcnt lgkmcnt(1)
	v_mfma_f32_32x32x16_bf16 v[114:129], v[130:133], v[134:137], v[114:129]
	v_mfma_f32_32x32x16_bf16 v[66:81], v[130:133], v[152:155], v[66:81]
	v_mfma_f32_32x32x16_bf16 v[34:49], v[130:133], v[164:167], v[34:49]
	v_mfma_f32_32x32x16_bf16 v[2:17], v[130:133], v[172:175], v[2:17]
	v_mfma_f32_32x32x16_bf16 v[98:113], v[138:141], v[142:145], v[98:113]
	v_mfma_f32_32x32x16_bf16 v[82:97], v[138:141], v[160:163], v[82:97]
	v_mfma_f32_32x32x16_bf16 v[50:65], v[138:141], v[168:171], v[50:65]
	v_mfma_f32_32x32x16_bf16 v[18:33], v[138:141], v[176:179], v[18:33]
	s_waitcnt lgkmcnt(0)
	v_mfma_f32_32x32x16_bf16 v[114:129], v[180:183], v[142:145], v[114:129]
	v_mfma_f32_32x32x16_bf16 v[66:81], v[180:183], v[160:163], v[66:81]
	v_mfma_f32_32x32x16_bf16 v[34:49], v[180:183], v[168:171], v[34:49]
	v_mfma_f32_32x32x16_bf16 v[2:17], v[180:183], v[176:179], v[2:17]
	s_barrier
	ds_read_b128 v[130:133], v148 offset:36864
	ds_read_b128 v[134:137], v147 offset:36864
	ds_read_b128 v[138:141], v148 offset:36896
	ds_read_b128 v[142:145], v147 offset:36896
	ds_read_b128 v[152:155], v147 offset:41472
	ds_read_b128 v[160:163], v147 offset:41504
	ds_read_b128 v[164:167], v147 offset:46080
	ds_read_b128 v[168:171], v147 offset:46112
	ds_read_b128 v[172:175], v147 offset:50688
	ds_read_b128 v[176:179], v147 offset:50720
	s_waitcnt lgkmcnt(8)
	v_mfma_f32_32x32x16_bf16 v[98:113], v[130:133], v[134:137], v[98:113]
	s_waitcnt lgkmcnt(5)
	v_mfma_f32_32x32x16_bf16 v[82:97], v[130:133], v[152:155], v[82:97]
	s_waitcnt lgkmcnt(3)
	v_mfma_f32_32x32x16_bf16 v[50:65], v[130:133], v[164:167], v[50:65]
	s_waitcnt lgkmcnt(1)
	v_mfma_f32_32x32x16_bf16 v[18:33], v[130:133], v[172:175], v[18:33]
	ds_read_b128 v[130:133], v148 offset:41472
	ds_read_b128 v[180:183], v148 offset:41504
	s_waitcnt lgkmcnt(1)
	v_mfma_f32_32x32x16_bf16 v[114:129], v[130:133], v[134:137], v[114:129]
	v_mfma_f32_32x32x16_bf16 v[66:81], v[130:133], v[152:155], v[66:81]
	v_mfma_f32_32x32x16_bf16 v[34:49], v[130:133], v[164:167], v[34:49]
	v_mfma_f32_32x32x16_bf16 v[2:17], v[130:133], v[172:175], v[2:17]
	v_mfma_f32_32x32x16_bf16 v[98:113], v[138:141], v[142:145], v[98:113]
	v_mfma_f32_32x32x16_bf16 v[82:97], v[138:141], v[160:163], v[82:97]
	v_mfma_f32_32x32x16_bf16 v[50:65], v[138:141], v[168:171], v[50:65]
	v_mfma_f32_32x32x16_bf16 v[18:33], v[138:141], v[176:179], v[18:33]
	s_waitcnt lgkmcnt(0)
;     ...
;     for (int ks = 0; ks < 4; ++ks) {
;       bf16x8 wf[2], xf[4];
; #pragma unroll
;       for (int ct = 0; ct < 2; ++ct) wf[ct] = *(const bf16x8*)(bs + ct * 32 * LD + ks * 16);
; #pragma unroll
;       for (int tt = 0; tt < 4; ++tt) xf[tt] = *(const bf16x8*)(as + tt * 32 * LD + ks * 16);
; #pragma unroll
;       for (int ct = 0; ct < 2; ++ct)
; #pragma unroll
;         for (int tt = 0; tt < 4; ++tt) acc[ct][tt] = __builtin_amdgcn_mfma_f32_32x32x16_bf16(wf[ct], xf[tt], acc[ct][tt], 0, 0, 0);
;     }
; __device__ void phase_gemm2(const Params& p, char* lds, int bid, int nb, bool fused) {
;     ...
;       for (int tt = 0; tt < 4; ++tt) {
;         const int tok = m0 + wr * 128 + tt * 32 + l31;
;         const float* xr = p.x + (size_t)tok * DM + n0 + wc * 64;
;         float ss = 0.f;
; #pragma unroll
;         for (int ct = 0; ct < 2; ++ct)
; #pragma unroll
;           for (int rq = 0; rq < 4; ++rq) {
;             const f32x4 xv = *(const f32x4*)(xr + ct * 32 + 8 * rq + 4 * h);
; #pragma unroll
;             for (int e = 0; e < 4; ++e) { acc[ct][tt][rq * 4 + e] += xv[e]; ss += acc[ct][tt][rq * 4 + e] * acc[ct][tt][rq * 4 + e]; }
;           }
;         ss += __shfl_xor(ss, 32);
;         olds[tt] = 0.f;
;         if (h == 0) olds[tt] = atomicAdd(p.ssq + tok, ss);
	v_mfma_f32_32x32x16_bf16 v[114:129], v[180:183], v[142:145], v[114:129]
	ds_read_b128 v[130:133], v148 offset:36928
	ds_read_b128 v[134:137], v147 offset:36928
	ds_read_b128 v[138:141], v148 offset:36960
	ds_read_b128 v[142:145], v147 offset:36960
	v_mfma_f32_32x32x16_bf16 v[66:81], v[180:183], v[160:163], v[66:81]
	ds_read_b128 v[152:155], v147 offset:41536
	ds_read_b128 v[160:163], v147 offset:41568
	v_mfma_f32_32x32x16_bf16 v[34:49], v[180:183], v[168:171], v[34:49]
	ds_read_b128 v[164:167], v147 offset:46144
	ds_read_b128 v[168:171], v147 offset:46176
	v_mfma_f32_32x32x16_bf16 v[2:17], v[180:183], v[176:179], v[2:17]
	ds_read_b128 v[172:175], v147 offset:50752
	ds_read_b128 v[176:179], v147 offset:50784
	s_waitcnt lgkmcnt(8)
	v_mfma_f32_32x32x16_bf16 v[98:113], v[130:133], v[134:137], v[98:113]
	s_waitcnt lgkmcnt(5)
	v_mfma_f32_32x32x16_bf16 v[82:97], v[130:133], v[152:155], v[82:97]
	s_waitcnt lgkmcnt(3)
	v_mfma_f32_32x32x16_bf16 v[50:65], v[130:133], v[164:167], v[50:65]
	s_waitcnt lgkmcnt(1)
	v_mfma_f32_32x32x16_bf16 v[18:33], v[130:133], v[172:175], v[18:33]
	ds_read_b128 v[130:133], v148 offset:41536
	ds_read_b128 v[180:183], v148 offset:41568
	s_waitcnt lgkmcnt(1)
	v_mfma_f32_32x32x16_bf16 v[114:129], v[130:133], v[134:137], v[114:129]
	v_mfma_f32_32x32x16_bf16 v[66:81], v[130:133], v[152:155], v[66:81]
	v_mfma_f32_32x32x16_bf16 v[34:49], v[130:133], v[164:167], v[34:49]
	v_mfma_f32_32x32x16_bf16 v[2:17], v[130:133], v[172:175], v[2:17]
	v_mfma_f32_32x32x16_bf16 v[98:113], v[138:141], v[142:145], v[98:113]
	v_mfma_f32_32x32x16_bf16 v[82:97], v[138:141], v[160:163], v[82:97]
	v_mfma_f32_32x32x16_bf16 v[50:65], v[138:141], v[168:171], v[50:65]
	v_mfma_f32_32x32x16_bf16 v[18:33], v[138:141], v[176:179], v[18:33]
	s_waitcnt lgkmcnt(0)
	v_mfma_f32_32x32x16_bf16 v[114:129], v[180:183], v[142:145], v[114:129]
	v_mfma_f32_32x32x16_bf16 v[66:81], v[180:183], v[160:163], v[66:81]
	v_mfma_f32_32x32x16_bf16 v[34:49], v[180:183], v[168:171], v[34:49]
	v_mfma_f32_32x32x16_bf16 v[2:17], v[180:183], v[176:179], v[2:17]
	s_andn2_b64 vcc, exec, s[12:13]
	s_cbranch_vccnz .Lp5_slow
	v_or_b32_e32 v130, s38, v146
	v_add_u32_e32 v152, s5, v130
	s_lshl_b32 s14, s4, 2
	s_lshl_b32 s36, s34, 2
	s_add_i32 s36, s36, s14
	v_lshl_add_u32 v162, v152, 12, v150
	v_lshlrev_b32_e32 v163, 2, v152
	s_add_u32 s54, s24, s36
	s_addc_u32 s55, s25, 0
	s_add_u32 s56, s54, 0x20000
	s_addc_u32 s57, s55, 0
	s_add_u32 s58, s54, 0x40000
	s_addc_u32 s59, s55, 0
	s_add_u32 s60, s54, 0x60000
	s_addc_u32 s61, s55, 0
	global_load_dwordx4 v[164:167], v162, s[54:55]
	global_load_dwordx4 v[168:171], v162, s[54:55] offset:32
	global_load_dwordx4 v[172:175], v162, s[54:55] offset:64
	global_load_dwordx4 v[176:179], v162, s[54:55] offset:96
	global_load_dwordx4 v[180:183], v162, s[54:55] offset:128
	global_load_dwordx4 v[184:187], v162, s[54:55] offset:160
	global_load_dwordx4 v[188:191], v162, s[54:55] offset:192
	global_load_dwordx4 v[192:195], v162, s[54:55] offset:224
	global_load_dwordx4 v[224:227], v162, s[56:57]
	global_load_dwordx4 v[228:231], v162, s[56:57] offset:32
	global_load_dwordx4 v[232:235], v162, s[56:57] offset:64
	global_load_dwordx4 v[236:239], v162, s[56:57] offset:96
	global_load_dwordx4 v[240:243], v162, s[56:57] offset:128
	global_load_dwordx4 v[244:247], v162, s[56:57] offset:160
	global_load_dwordx4 v[248:251], v162, s[56:57] offset:192
	global_load_dwordx4 v[252:255], v162, s[56:57] offset:224
	global_load_dwordx4 v[196:199], v162, s[58:59]
	global_load_dwordx4 v[200:203], v162, s[58:59] offset:32
	global_load_dwordx4 v[204:207], v162, s[58:59] offset:64
	global_load_dwordx4 v[208:211], v162, s[58:59] offset:96
	global_load_dwordx4 v[212:215], v162, s[58:59] offset:128
	global_load_dwordx4 v[216:219], v162, s[58:59] offset:160
	global_load_dwordx4 v[130:133], v162, s[58:59] offset:192
	global_load_dwordx4 v[134:137], v162, s[58:59] offset:224
	v_mbcnt_lo_u32_b32 v160, -1, 0
	v_mbcnt_hi_u32_b32 v160, -1, v160
	v_xor_b32_e32 v160, 32, v160
	v_lshlrev_b32_e32 v160, 2, v160
	v_cmp_eq_u32_e64 s[62:63], 0, v159
	s_add_u32 s66, s8, s36
	s_addc_u32 s67, s9, 0
	s_waitcnt vmcnt(16)
	v_pk_add_f32 v[98:99], v[98:99], v[164:165]
	v_pk_add_f32 v[100:101], v[100:101], v[166:167]
	v_pk_add_f32 v[102:103], v[102:103], v[168:169]
	v_pk_add_f32 v[104:105], v[104:105], v[170:171]
	v_pk_add_f32 v[106:107], v[106:107], v[172:173]
	v_pk_add_f32 v[108:109], v[108:109], v[174:175]
	v_pk_add_f32 v[110:111], v[110:111], v[176:177]
	v_pk_add_f32 v[112:113], v[112:113], v[178:179]
	v_pk_add_f32 v[114:115], v[114:115], v[180:181]
	v_pk_add_f32 v[116:117], v[116:117], v[182:183]
	v_pk_add_f32 v[118:119], v[118:119], v[184:185]
	v_pk_add_f32 v[120:121], v[120:121], v[186:187]
	v_pk_add_f32 v[122:123], v[122:123], v[188:189]
	v_pk_add_f32 v[124:125], v[124:125], v[190:191]
	v_pk_add_f32 v[126:127], v[126:127], v[192:193]
	v_pk_add_f32 v[128:129], v[128:129], v[194:195]
	v_pk_mul_f32 v[146:147], v[98:99], v[98:99]
	v_add_f32_e32 v161, v146, v147
	v_pk_mul_f32 v[148:149], v[100:101], v[100:101]
	v_add_f32_e32 v161, v148, v161
	v_add_f32_e32 v161, v149, v161
	v_pk_mul_f32 v[146:147], v[102:103], v[102:103]
	v_add_f32_e32 v161, v146, v161
	v_add_f32_e32 v161, v147, v161
	v_pk_mul_f32 v[148:149], v[104:105], v[104:105]
	v_add_f32_e32 v161, v148, v161
	v_add_f32_e32 v161, v149, v161
	v_pk_mul_f32 v[146:147], v[106:107], v[106:107]
	v_add_f32_e32 v161, v146, v161
	v_add_f32_e32 v161, v147, v161
	v_pk_mul_f32 v[148:149], v[108:109], v[108:109]
	v_add_f32_e32 v161, v148, v161
	v_add_f32_e32 v161, v149, v161
	v_pk_mul_f32 v[146:147], v[110:111], v[110:111]
	v_add_f32_e32 v161, v146, v161
	v_add_f32_e32 v161, v147, v161
	v_pk_mul_f32 v[148:149], v[112:113], v[112:113]
	v_add_f32_e32 v161, v148, v161
	v_add_f32_e32 v161, v149, v161
	v_pk_mul_f32 v[146:147], v[114:115], v[114:115]
	v_add_f32_e32 v161, v146, v161
	v_add_f32_e32 v161, v147, v161
	v_pk_mul_f32 v[148:149], v[116:117], v[116:117]
	v_add_f32_e32 v161, v148, v161
	v_add_f32_e32 v161, v149, v161
	v_pk_mul_f32 v[146:147], v[118:119], v[118:119]
	v_add_f32_e32 v161, v146, v161
	v_add_f32_e32 v161, v147, v161
	v_pk_mul_f32 v[148:149], v[120:121], v[120:121]
	v_add_f32_e32 v161, v148, v161
	v_add_f32_e32 v161, v149, v161
	v_pk_mul_f32 v[146:147], v[122:123], v[122:123]
	v_add_f32_e32 v161, v146, v161
	v_add_f32_e32 v161, v147, v161
	v_pk_mul_f32 v[148:149], v[124:125], v[124:125]
	v_add_f32_e32 v161, v148, v161
	v_add_f32_e32 v161, v149, v161
	v_pk_mul_f32 v[146:147], v[126:127], v[126:127]
	v_add_f32_e32 v161, v146, v161
	v_add_f32_e32 v161, v147, v161
	v_pk_mul_f32 v[148:149], v[128:129], v[128:129]
	v_add_f32_e32 v161, v148, v161
	v_add_f32_e32 v161, v149, v161
	ds_bpermute_b32 v146, v160, v161
	s_waitcnt lgkmcnt(0)
; __device__ void phase_gemm2(const Params& p, char* lds, int bid, int nb, bool fused) {
;     ...
;       for (int tt = 0; tt < 4; ++tt) {
;         const int tok = m0 + wr * 128 + tt * 32 + l31;
;         const float* xr = p.x + (size_t)tok * DM + n0 + wc * 64;
;         float ss = 0.f;
; #pragma unroll
;         for (int ct = 0; ct < 2; ++ct)
; #pragma unroll
;           for (int rq = 0; rq < 4; ++rq) {
;             const f32x4 xv = *(const f32x4*)(xr + ct * 32 + 8 * rq + 4 * h);
; #pragma unroll
;             for (int e = 0; e < 4; ++e) { acc[ct][tt][rq * 4 + e] += xv[e]; ss += acc[ct][tt][rq * 4 + e] * acc[ct][tt][rq * 4 + e]; }
;           }
;         ss += __shfl_xor(ss, 32);
;         olds[tt] = 0.f;
;         if (h == 0) olds[tt] = atomicAdd(p.ssq + tok, ss);
	v_add_f32_e32 v161, v161, v146
	s_and_saveexec_b64 s[64:65], s[62:63]
	global_atomic_add_f32 v139, v163, v161, s[18:19] sc0
	s_or_b64 exec, exec, s[64:65]
	global_load_dwordx4 v[164:167], v162, s[60:61]
	global_load_dwordx4 v[168:171], v162, s[60:61] offset:32
	global_load_dwordx4 v[172:175], v162, s[60:61] offset:64
	global_load_dwordx4 v[176:179], v162, s[60:61] offset:96
	global_load_dwordx4 v[180:183], v162, s[60:61] offset:128
	global_load_dwordx4 v[184:187], v162, s[60:61] offset:160
	global_load_dwordx4 v[188:191], v162, s[60:61] offset:192
	global_load_dwordx4 v[192:195], v162, s[60:61] offset:224
	s_waitcnt vmcnt(17)
	v_pk_add_f32 v[82:83], v[82:83], v[224:225]
	v_pk_add_f32 v[84:85], v[84:85], v[226:227]
	v_pk_add_f32 v[86:87], v[86:87], v[228:229]
	v_pk_add_f32 v[88:89], v[88:89], v[230:231]
	v_pk_add_f32 v[90:91], v[90:91], v[232:233]
	v_pk_add_f32 v[92:93], v[92:93], v[234:235]
	v_pk_add_f32 v[94:95], v[94:95], v[236:237]
	v_pk_add_f32 v[96:97], v[96:97], v[238:239]
	v_pk_add_f32 v[66:67], v[66:67], v[240:241]
	v_pk_add_f32 v[68:69], v[68:69], v[242:243]
	v_pk_add_f32 v[70:71], v[70:71], v[244:245]
	v_pk_add_f32 v[72:73], v[72:73], v[246:247]
	v_pk_add_f32 v[74:75], v[74:75], v[248:249]
	v_pk_add_f32 v[76:77], v[76:77], v[250:251]
	v_pk_add_f32 v[78:79], v[78:79], v[252:253]
	v_pk_add_f32 v[80:81], v[80:81], v[254:255]
	v_pk_mul_f32 v[146:147], v[82:83], v[82:83]
	v_add_f32_e32 v220, v146, v147
	v_pk_mul_f32 v[148:149], v[84:85], v[84:85]
	v_add_f32_e32 v220, v148, v220
	v_add_f32_e32 v220, v149, v220
	v_pk_mul_f32 v[146:147], v[86:87], v[86:87]
	v_add_f32_e32 v220, v146, v220
	v_add_f32_e32 v220, v147, v220
	v_pk_mul_f32 v[148:149], v[88:89], v[88:89]
	v_add_f32_e32 v220, v148, v220
	v_add_f32_e32 v220, v149, v220
	v_pk_mul_f32 v[146:147], v[90:91], v[90:91]
	v_add_f32_e32 v220, v146, v220
	v_add_f32_e32 v220, v147, v220
	v_pk_mul_f32 v[148:149], v[92:93], v[92:93]
	v_add_f32_e32 v220, v148, v220
	v_add_f32_e32 v220, v149, v220
	v_pk_mul_f32 v[146:147], v[94:95], v[94:95]
	v_add_f32_e32 v220, v146, v220
	v_add_f32_e32 v220, v147, v220
	v_pk_mul_f32 v[148:149], v[96:97], v[96:97]
	v_add_f32_e32 v220, v148, v220
	v_add_f32_e32 v220, v149, v220
	v_pk_mul_f32 v[146:147], v[66:67], v[66:67]
	v_add_f32_e32 v220, v146, v220
	v_add_f32_e32 v220, v147, v220
	v_pk_mul_f32 v[148:149], v[68:69], v[68:69]
	v_add_f32_e32 v220, v148, v220
	v_add_f32_e32 v220, v149, v220
	v_pk_mul_f32 v[146:147], v[70:71], v[70:71]
	v_add_f32_e32 v220, v146, v220
	v_add_f32_e32 v220, v147, v220
	v_pk_mul_f32 v[148:149], v[72:73], v[72:73]
	v_add_f32_e32 v220, v148, v220
	v_add_f32_e32 v220, v149, v220
	v_pk_mul_f32 v[146:147], v[74:75], v[74:75]
	v_add_f32_e32 v220, v146, v220
	v_add_f32_e32 v220, v147, v220
	v_pk_mul_f32 v[148:149], v[76:77], v[76:77]
	v_add_f32_e32 v220, v148, v220
	v_add_f32_e32 v220, v149, v220
	v_pk_mul_f32 v[146:147], v[78:79], v[78:79]
	v_add_f32_e32 v220, v146, v220
	v_add_f32_e32 v220, v147, v220
	v_pk_mul_f32 v[148:149], v[80:81], v[80:81]
	v_add_f32_e32 v220, v148, v220
	v_add_f32_e32 v220, v149, v220
	ds_bpermute_b32 v146, v160, v220
	s_waitcnt lgkmcnt(0)
	v_add_f32_e32 v220, v220, v146
	s_and_saveexec_b64 s[64:65], s[62:63]
	global_atomic_add_f32 v141, v163, v220, s[18:19] offset:128 sc0
	s_or_b64 exec, exec, s[64:65]
	global_load_dwordx4 v[224:227], v150, s[66:67]
	global_load_dwordx4 v[228:231], v150, s[66:67] offset:32
	global_load_dwordx4 v[232:235], v150, s[66:67] offset:64
	global_load_dwordx4 v[236:239], v150, s[66:67] offset:96
	global_load_dwordx4 v[240:243], v150, s[66:67] offset:128
	global_load_dwordx4 v[244:247], v150, s[66:67] offset:160
	global_load_dwordx4 v[248:251], v150, s[66:67] offset:192
	global_load_dwordx4 v[252:255], v150, s[66:67] offset:224
	s_waitcnt vmcnt(18)
	v_pk_add_f32 v[50:51], v[50:51], v[196:197]
	v_pk_add_f32 v[52:53], v[52:53], v[198:199]
	v_pk_add_f32 v[54:55], v[54:55], v[200:201]
	v_pk_add_f32 v[56:57], v[56:57], v[202:203]
	v_pk_add_f32 v[58:59], v[58:59], v[204:205]
	v_pk_add_f32 v[60:61], v[60:61], v[206:207]
	v_pk_add_f32 v[62:63], v[62:63], v[208:209]
	v_pk_add_f32 v[64:65], v[64:65], v[210:211]
	v_pk_add_f32 v[34:35], v[34:35], v[212:213]
	v_pk_add_f32 v[36:37], v[36:37], v[214:215]
	v_pk_add_f32 v[38:39], v[38:39], v[216:217]
	v_pk_add_f32 v[40:41], v[40:41], v[218:219]
	v_pk_add_f32 v[42:43], v[42:43], v[130:131]
	v_pk_add_f32 v[44:45], v[44:45], v[132:133]
	v_pk_add_f32 v[46:47], v[46:47], v[134:135]
	v_pk_add_f32 v[48:49], v[48:49], v[136:137]
	v_pk_mul_f32 v[146:147], v[50:51], v[50:51]
	v_add_f32_e32 v221, v146, v147
	v_pk_mul_f32 v[148:149], v[52:53], v[52:53]
	v_add_f32_e32 v221, v148, v221
	v_add_f32_e32 v221, v149, v221
	v_pk_mul_f32 v[146:147], v[54:55], v[54:55]
	v_add_f32_e32 v221, v146, v221
	v_add_f32_e32 v221, v147, v221
	v_pk_mul_f32 v[148:149], v[56:57], v[56:57]
	v_add_f32_e32 v221, v148, v221
	v_add_f32_e32 v221, v149, v221
	v_pk_mul_f32 v[146:147], v[58:59], v[58:59]
	v_add_f32_e32 v221, v146, v221
	v_add_f32_e32 v221, v147, v221
	v_pk_mul_f32 v[148:149], v[60:61], v[60:61]
	v_add_f32_e32 v221, v148, v221
	v_add_f32_e32 v221, v149, v221
	v_pk_mul_f32 v[146:147], v[62:63], v[62:63]
	v_add_f32_e32 v221, v146, v221
	v_add_f32_e32 v221, v147, v221
	v_pk_mul_f32 v[148:149], v[64:65], v[64:65]
	v_add_f32_e32 v221, v148, v221
	v_add_f32_e32 v221, v149, v221
	v_pk_mul_f32 v[146:147], v[34:35], v[34:35]
	v_add_f32_e32 v221, v146, v221
	v_add_f32_e32 v221, v147, v221
	v_pk_mul_f32 v[148:149], v[36:37], v[36:37]
	v_add_f32_e32 v221, v148, v221
	v_add_f32_e32 v221, v149, v221
	v_pk_mul_f32 v[146:147], v[38:39], v[38:39]
	v_add_f32_e32 v221, v146, v221
	v_add_f32_e32 v221, v147, v221
	v_pk_mul_f32 v[148:149], v[40:41], v[40:41]
	v_add_f32_e32 v221, v148, v221
	v_add_f32_e32 v221, v149, v221
	v_pk_mul_f32 v[146:147], v[42:43], v[42:43]
	v_add_f32_e32 v221, v146, v221
	v_add_f32_e32 v221, v147, v221
	v_pk_mul_f32 v[148:149], v[44:45], v[44:45]
	v_add_f32_e32 v221, v148, v221
	v_add_f32_e32 v221, v149, v221
	v_pk_mul_f32 v[146:147], v[46:47], v[46:47]
	v_add_f32_e32 v221, v146, v221
	v_add_f32_e32 v221, v147, v221
	v_pk_mul_f32 v[148:149], v[48:49], v[48:49]
	v_add_f32_e32 v221, v148, v221
	v_add_f32_e32 v221, v149, v221
	ds_bpermute_b32 v146, v160, v221
	s_waitcnt lgkmcnt(0)
; __device__ void phase_gemm2(const Params& p, char* lds, int bid, int nb, bool fused) {
;     ...
;       for (int tt = 0; tt < 4; ++tt) {
;         const int tok = m0 + wr * 128 + tt * 32 + l31;
;         const float* xr = p.x + (size_t)tok * DM + n0 + wc * 64;
;         float ss = 0.f;
; #pragma unroll
;         for (int ct = 0; ct < 2; ++ct)
; #pragma unroll
;           for (int rq = 0; rq < 4; ++rq) {
;             const f32x4 xv = *(const f32x4*)(xr + ct * 32 + 8 * rq + 4 * h);
; #pragma unroll
;             for (int e = 0; e < 4; ++e) { acc[ct][tt][rq * 4 + e] += xv[e]; ss += acc[ct][tt][rq * 4 + e] * acc[ct][tt][rq * 4 + e]; }
;           }
;         ss += __shfl_xor(ss, 32);
;         olds[tt] = 0.f;
;         if (h == 0) olds[tt] = atomicAdd(p.ssq + tok, ss);
;       }
;       asm volatile("" :: "v"(olds[0]), "v"(olds[1]), "v"(olds[2]), "v"(olds[3]));
;       if (fused) {
;         __syncthreads();
;         if (threadIdx.x == 0) {
;           __hip_atomic_fetch_add(p.pcnt + (m0 >> 8), 1, __ATOMIC_RELAXED, __HIP_MEMORY_SCOPE_AGENT);
;           while (__hip_atomic_load(p.pcnt + (m0 >> 8), __ATOMIC_RELAXED, __HIP_MEMORY_SCOPE_AGENT) < NNT) __builtin_amdgcn_s_sleep(2);
;         }
;         __syncthreads();
;       }
; #pragma unroll
;       for (int tt = 0; tt < 4; ++tt) {
;         const int tok = m0 + wr * 128 + tt * 32 + l31;
;         float sc = 1.f;
;         if (fused) sc = __builtin_amdgcn_rsqf(__hip_atomic_load(p.ssq + tok, __ATOMIC_RELAXED, __HIP_MEMORY_SCOPE_AGENT) * (1.f / DM) + 1e-6f);
	v_add_f32_e32 v221, v221, v146
	s_and_saveexec_b64 s[64:65], s[62:63]
	global_atomic_add_f32 v143, v163, v221, s[18:19] offset:256 sc0
	s_or_b64 exec, exec, s[64:65]
	s_waitcnt vmcnt(10)
	v_pk_add_f32 v[18:19], v[18:19], v[164:165]
	v_pk_add_f32 v[20:21], v[20:21], v[166:167]
	v_pk_add_f32 v[22:23], v[22:23], v[168:169]
	v_pk_add_f32 v[24:25], v[24:25], v[170:171]
	v_pk_add_f32 v[26:27], v[26:27], v[172:173]
	v_pk_add_f32 v[28:29], v[28:29], v[174:175]
	v_pk_add_f32 v[30:31], v[30:31], v[176:177]
	v_pk_add_f32 v[32:33], v[32:33], v[178:179]
	v_pk_add_f32 v[2:3], v[2:3], v[180:181]
	v_pk_add_f32 v[4:5], v[4:5], v[182:183]
	v_pk_add_f32 v[6:7], v[6:7], v[184:185]
	v_pk_add_f32 v[8:9], v[8:9], v[186:187]
	v_pk_add_f32 v[10:11], v[10:11], v[188:189]
	v_pk_add_f32 v[12:13], v[12:13], v[190:191]
	v_pk_add_f32 v[14:15], v[14:15], v[192:193]
	v_pk_add_f32 v[16:17], v[16:17], v[194:195]
	v_pk_mul_f32 v[146:147], v[18:19], v[18:19]
	v_add_f32_e32 v222, v146, v147
	v_pk_mul_f32 v[148:149], v[20:21], v[20:21]
	v_add_f32_e32 v222, v148, v222
	v_add_f32_e32 v222, v149, v222
	v_pk_mul_f32 v[146:147], v[22:23], v[22:23]
	v_add_f32_e32 v222, v146, v222
	v_add_f32_e32 v222, v147, v222
	v_pk_mul_f32 v[148:149], v[24:25], v[24:25]
	v_add_f32_e32 v222, v148, v222
	v_add_f32_e32 v222, v149, v222
	v_pk_mul_f32 v[146:147], v[26:27], v[26:27]
	v_add_f32_e32 v222, v146, v222
	v_add_f32_e32 v222, v147, v222
	v_pk_mul_f32 v[148:149], v[28:29], v[28:29]
	v_add_f32_e32 v222, v148, v222
	v_add_f32_e32 v222, v149, v222
	v_pk_mul_f32 v[146:147], v[30:31], v[30:31]
	v_add_f32_e32 v222, v146, v222
	v_add_f32_e32 v222, v147, v222
	v_pk_mul_f32 v[148:149], v[32:33], v[32:33]
	v_add_f32_e32 v222, v148, v222
	v_add_f32_e32 v222, v149, v222
	v_pk_mul_f32 v[146:147], v[2:3], v[2:3]
	v_add_f32_e32 v222, v146, v222
	v_add_f32_e32 v222, v147, v222
	v_pk_mul_f32 v[148:149], v[4:5], v[4:5]
	v_add_f32_e32 v222, v148, v222
	v_add_f32_e32 v222, v149, v222
	v_pk_mul_f32 v[146:147], v[6:7], v[6:7]
	v_add_f32_e32 v222, v146, v222
	v_add_f32_e32 v222, v147, v222
	v_pk_mul_f32 v[148:149], v[8:9], v[8:9]
	v_add_f32_e32 v222, v148, v222
	v_add_f32_e32 v222, v149, v222
	v_pk_mul_f32 v[146:147], v[10:11], v[10:11]
	v_add_f32_e32 v222, v146, v222
	v_add_f32_e32 v222, v147, v222
	v_pk_mul_f32 v[148:149], v[12:13], v[12:13]
	v_add_f32_e32 v222, v148, v222
	v_add_f32_e32 v222, v149, v222
	v_pk_mul_f32 v[146:147], v[14:15], v[14:15]
	v_add_f32_e32 v222, v146, v222
	v_add_f32_e32 v222, v147, v222
	v_pk_mul_f32 v[148:149], v[16:17], v[16:17]
	v_add_f32_e32 v222, v148, v222
	v_add_f32_e32 v222, v149, v222
	ds_bpermute_b32 v146, v160, v222
	s_waitcnt lgkmcnt(0)
	v_add_f32_e32 v222, v222, v146
	s_and_saveexec_b64 s[64:65], s[62:63]
	global_atomic_add_f32 v145, v163, v222, s[18:19] offset:384 sc0
	s_or_b64 exec, exec, s[64:65]
	s_waitcnt vmcnt(0)
	s_barrier
	s_and_saveexec_b64 s[64:65], s[48:49]
	s_cbranch_execz .Lp5_pollend
	s_ashr_i32 s38, s38, 8
	s_mov_b64 s[40:41], exec
	s_ashr_i32 s39, s38, 31
	s_lshl_b64 s[38:39], s[38:39], 2
	v_mbcnt_lo_u32_b32 v146, s40, 0
	s_add_u32 s38, s20, s38
	v_mbcnt_hi_u32_b32 v146, s41, v146
	s_addc_u32 s39, s21, s39
	v_cmp_eq_u32_e32 vcc, 0, v146
	s_and_saveexec_b64 s[42:43], vcc
	s_cbranch_execz .Lp5_noinc
	s_bcnt1_i32_b64 s40, s[40:41]
	v_mov_b32_e32 v146, s40
	global_atomic_add v151, v146, s[38:39]
.Lp5_noinc:
	s_or_b64 exec, exec, s[42:43]
	global_load_dword v146, v151, s[38:39] sc1
	s_waitcnt vmcnt(0)
	v_cmp_lt_i32_e32 vcc, 3, v146
	s_cbranch_vccnz .Lp5_pollend
.Lp5_poll:
	s_sleep 2
	global_load_dword v146, v151, s[38:39] sc1
	s_waitcnt vmcnt(0)
	v_cmp_gt_i32_e32 vcc, 4, v146
	s_cbranch_vccnz .Lp5_poll
.Lp5_pollend:
	s_or_b64 exec, exec, s[64:65]
	s_barrier
	global_load_dword v138, v163, s[18:19] sc1
	global_load_dword v140, v163, s[18:19] offset:128 sc1
	global_load_dword v142, v163, s[18:19] offset:256 sc1
	global_load_dword v144, v163, s[18:19] offset:384 sc1
	s_add_u32 s54, s10, s36
	s_addc_u32 s55, s11, 0
	s_add_u32 s56, s54, 0x20000
	s_addc_u32 s57, s55, 0
	s_add_u32 s58, s54, 0x40000
	s_addc_u32 s59, s55, 0
	s_add_u32 s60, s54, 0x60000
	s_addc_u32 s61, s55, 0
	s_waitcnt vmcnt(3)
	v_fmamk_f32 v138, v138, 0x3a800000, v158
	v_rsq_f32_e32 v138, v138
	s_waitcnt vmcnt(2)
	v_fmamk_f32 v140, v140, 0x3a800000, v158
	v_rsq_f32_e32 v140, v140
	s_waitcnt vmcnt(1)
	v_fmamk_f32 v142, v142, 0x3a800000, v158
	v_rsq_f32_e32 v142, v142
	s_waitcnt vmcnt(0)
; __device__ void phase_gemm2(const Params& p, char* lds, int bid, int nb, bool fused) {
;     ...
; #pragma unroll
;       for (int tt = 0; tt < 4; ++tt) {
;         const int tok = m0 + wr * 128 + tt * 32 + l31;
;         float sc = 1.f;
;         if (fused) sc = __builtin_amdgcn_rsqf(__hip_atomic_load(p.ssq + tok, __ATOMIC_RELAXED, __HIP_MEMORY_SCOPE_AGENT) * (1.f / DM) + 1e-6f);
;         float* orow = p.out + (size_t)tok * DM + n0 + wc * 64;
;         const float* gr = p.final_gain + n0 + wc * 64;
; #pragma unroll
;         for (int ct = 0; ct < 2; ++ct)
; #pragma unroll
;           for (int rq = 0; rq < 4; ++rq) {
;             const int c = ct * 32 + 8 * rq + 4 * h;
;             f32x4 o;
;             if (fused) {
;               const f32x4 gv = *(const f32x4*)(gr + c);
; #pragma unroll
;               for (int e = 0; e < 4; ++e) o[e] = acc[ct][tt][rq * 4 + e] * sc * gv[e];
;             } else {
; #pragma unroll
;               for (int e = 0; e < 4; ++e) o[e] = acc[ct][tt][rq * 4 + e];
;             }
;             *(f32x4*)(orow + c) = o;
;           }
	v_fmamk_f32 v144, v144, 0x3a800000, v158
	v_rsq_f32_e32 v144, v144
	s_nop 0
	v_pk_mul_f32 v[98:99], v[98:99], v[138:139] op_sel_hi:[1,0]
	v_pk_mul_f32 v[100:101], v[100:101], v[138:139] op_sel_hi:[1,0]
	v_pk_mul_f32 v[98:99], v[98:99], v[224:225]
	v_pk_mul_f32 v[100:101], v[100:101], v[226:227]
	global_store_dwordx4 v162, v[98:101], s[54:55]
	v_pk_mul_f32 v[102:103], v[102:103], v[138:139] op_sel_hi:[1,0]
	v_pk_mul_f32 v[104:105], v[104:105], v[138:139] op_sel_hi:[1,0]
	v_pk_mul_f32 v[102:103], v[102:103], v[228:229]
	v_pk_mul_f32 v[104:105], v[104:105], v[230:231]
	global_store_dwordx4 v162, v[102:105], s[54:55] offset:32
	v_pk_mul_f32 v[106:107], v[106:107], v[138:139] op_sel_hi:[1,0]
	v_pk_mul_f32 v[108:109], v[108:109], v[138:139] op_sel_hi:[1,0]
	v_pk_mul_f32 v[106:107], v[106:107], v[232:233]
	v_pk_mul_f32 v[108:109], v[108:109], v[234:235]
	global_store_dwordx4 v162, v[106:109], s[54:55] offset:64
	v_pk_mul_f32 v[110:111], v[110:111], v[138:139] op_sel_hi:[1,0]
	v_pk_mul_f32 v[112:113], v[112:113], v[138:139] op_sel_hi:[1,0]
	v_pk_mul_f32 v[110:111], v[110:111], v[236:237]
	v_pk_mul_f32 v[112:113], v[112:113], v[238:239]
	global_store_dwordx4 v162, v[110:113], s[54:55] offset:96
	v_pk_mul_f32 v[114:115], v[114:115], v[138:139] op_sel_hi:[1,0]
	v_pk_mul_f32 v[116:117], v[116:117], v[138:139] op_sel_hi:[1,0]
	v_pk_mul_f32 v[114:115], v[114:115], v[240:241]
	v_pk_mul_f32 v[116:117], v[116:117], v[242:243]
	global_store_dwordx4 v162, v[114:117], s[54:55] offset:128
	v_pk_mul_f32 v[118:119], v[118:119], v[138:139] op_sel_hi:[1,0]
	v_pk_mul_f32 v[120:121], v[120:121], v[138:139] op_sel_hi:[1,0]
	v_pk_mul_f32 v[118:119], v[118:119], v[244:245]
	v_pk_mul_f32 v[120:121], v[120:121], v[246:247]
	global_store_dwordx4 v162, v[118:121], s[54:55] offset:160
	v_pk_mul_f32 v[122:123], v[122:123], v[138:139] op_sel_hi:[1,0]
	v_pk_mul_f32 v[124:125], v[124:125], v[138:139] op_sel_hi:[1,0]
	v_pk_mul_f32 v[122:123], v[122:123], v[248:249]
	v_pk_mul_f32 v[124:125], v[124:125], v[250:251]
	global_store_dwordx4 v162, v[122:125], s[54:55] offset:192
	v_pk_mul_f32 v[126:127], v[126:127], v[138:139] op_sel_hi:[1,0]
	v_pk_mul_f32 v[128:129], v[128:129], v[138:139] op_sel_hi:[1,0]
	v_pk_mul_f32 v[126:127], v[126:127], v[252:253]
	v_pk_mul_f32 v[128:129], v[128:129], v[254:255]
	global_store_dwordx4 v162, v[126:129], s[54:55] offset:224
	v_pk_mul_f32 v[82:83], v[82:83], v[140:141] op_sel_hi:[1,0]
	v_pk_mul_f32 v[84:85], v[84:85], v[140:141] op_sel_hi:[1,0]
	v_pk_mul_f32 v[82:83], v[82:83], v[224:225]
	v_pk_mul_f32 v[84:85], v[84:85], v[226:227]
	global_store_dwordx4 v162, v[82:85], s[56:57]
	v_pk_mul_f32 v[86:87], v[86:87], v[140:141] op_sel_hi:[1,0]
	v_pk_mul_f32 v[88:89], v[88:89], v[140:141] op_sel_hi:[1,0]
	v_pk_mul_f32 v[86:87], v[86:87], v[228:229]
	v_pk_mul_f32 v[88:89], v[88:89], v[230:231]
	global_store_dwordx4 v162, v[86:89], s[56:57] offset:32
	v_pk_mul_f32 v[90:91], v[90:91], v[140:141] op_sel_hi:[1,0]
	v_pk_mul_f32 v[92:93], v[92:93], v[140:141] op_sel_hi:[1,0]
	v_pk_mul_f32 v[90:91], v[90:91], v[232:233]
	v_pk_mul_f32 v[92:93], v[92:93], v[234:235]
	global_store_dwordx4 v162, v[90:93], s[56:57] offset:64
	v_pk_mul_f32 v[94:95], v[94:95], v[140:141] op_sel_hi:[1,0]
	v_pk_mul_f32 v[96:97], v[96:97], v[140:141] op_sel_hi:[1,0]
	v_pk_mul_f32 v[94:95], v[94:95], v[236:237]
	v_pk_mul_f32 v[96:97], v[96:97], v[238:239]
	global_store_dwordx4 v162, v[94:97], s[56:57] offset:96
	v_pk_mul_f32 v[66:67], v[66:67], v[140:141] op_sel_hi:[1,0]
	v_pk_mul_f32 v[68:69], v[68:69], v[140:141] op_sel_hi:[1,0]
	v_pk_mul_f32 v[66:67], v[66:67], v[240:241]
	v_pk_mul_f32 v[68:69], v[68:69], v[242:243]
	global_store_dwordx4 v162, v[66:69], s[56:57] offset:128
	v_pk_mul_f32 v[70:71], v[70:71], v[140:141] op_sel_hi:[1,0]
	v_pk_mul_f32 v[72:73], v[72:73], v[140:141] op_sel_hi:[1,0]
	v_pk_mul_f32 v[70:71], v[70:71], v[244:245]
	v_pk_mul_f32 v[72:73], v[72:73], v[246:247]
	global_store_dwordx4 v162, v[70:73], s[56:57] offset:160
	v_pk_mul_f32 v[74:75], v[74:75], v[140:141] op_sel_hi:[1,0]
	v_pk_mul_f32 v[76:77], v[76:77], v[140:141] op_sel_hi:[1,0]
	v_pk_mul_f32 v[74:75], v[74:75], v[248:249]
	v_pk_mul_f32 v[76:77], v[76:77], v[250:251]
	global_store_dwordx4 v162, v[74:77], s[56:57] offset:192
	v_pk_mul_f32 v[78:79], v[78:79], v[140:141] op_sel_hi:[1,0]
	v_pk_mul_f32 v[80:81], v[80:81], v[140:141] op_sel_hi:[1,0]
	v_pk_mul_f32 v[78:79], v[78:79], v[252:253]
	v_pk_mul_f32 v[80:81], v[80:81], v[254:255]
	global_store_dwordx4 v162, v[78:81], s[56:57] offset:224
	v_pk_mul_f32 v[50:51], v[50:51], v[142:143] op_sel_hi:[1,0]
	v_pk_mul_f32 v[52:53], v[52:53], v[142:143] op_sel_hi:[1,0]
	v_pk_mul_f32 v[50:51], v[50:51], v[224:225]
	v_pk_mul_f32 v[52:53], v[52:53], v[226:227]
	global_store_dwordx4 v162, v[50:53], s[58:59]
	v_pk_mul_f32 v[54:55], v[54:55], v[142:143] op_sel_hi:[1,0]
	v_pk_mul_f32 v[56:57], v[56:57], v[142:143] op_sel_hi:[1,0]
	v_pk_mul_f32 v[54:55], v[54:55], v[228:229]
	v_pk_mul_f32 v[56:57], v[56:57], v[230:231]
	global_store_dwordx4 v162, v[54:57], s[58:59] offset:32
	v_pk_mul_f32 v[58:59], v[58:59], v[142:143] op_sel_hi:[1,0]
	v_pk_mul_f32 v[60:61], v[60:61], v[142:143] op_sel_hi:[1,0]
	v_pk_mul_f32 v[58:59], v[58:59], v[232:233]
	v_pk_mul_f32 v[60:61], v[60:61], v[234:235]
	global_store_dwordx4 v162, v[58:61], s[58:59] offset:64
	v_pk_mul_f32 v[62:63], v[62:63], v[142:143] op_sel_hi:[1,0]
	v_pk_mul_f32 v[64:65], v[64:65], v[142:143] op_sel_hi:[1,0]
	v_pk_mul_f32 v[62:63], v[62:63], v[236:237]
	v_pk_mul_f32 v[64:65], v[64:65], v[238:239]
	global_store_dwordx4 v162, v[62:65], s[58:59] offset:96
	v_pk_mul_f32 v[34:35], v[34:35], v[142:143] op_sel_hi:[1,0]
; __device__ void phase_gemm2(const Params& p, char* lds, int bid, int nb, bool fused) {
;     ...
;   for (int Lx = jx; Lx < (NMT / 8) * NNT; Lx += nbx) {
;     ...
; #pragma unroll
;       for (int tt = 0; tt < 4; ++tt) {
;         const int tok = m0 + wr * 128 + tt * 32 + l31;
;         float sc = 1.f;
;         if (fused) sc = __builtin_amdgcn_rsqf(__hip_atomic_load(p.ssq + tok, __ATOMIC_RELAXED, __HIP_MEMORY_SCOPE_AGENT) * (1.f / DM) + 1e-6f);
;         float* orow = p.out + (size_t)tok * DM + n0 + wc * 64;
;         const float* gr = p.final_gain + n0 + wc * 64;
; #pragma unroll
;         for (int ct = 0; ct < 2; ++ct)
; #pragma unroll
;           for (int rq = 0; rq < 4; ++rq) {
;             const int c = ct * 32 + 8 * rq + 4 * h;
;             f32x4 o;
;             if (fused) {
;               const f32x4 gv = *(const f32x4*)(gr + c);
; #pragma unroll
;               for (int e = 0; e < 4; ++e) o[e] = acc[ct][tt][rq * 4 + e] * sc * gv[e];
;             } else {
; #pragma unroll
;               for (int e = 0; e < 4; ++e) o[e] = acc[ct][tt][rq * 4 + e];
;             }
;             *(f32x4*)(orow + c) = o;
;           }
;       }
;     });
	v_pk_mul_f32 v[36:37], v[36:37], v[142:143] op_sel_hi:[1,0]
	v_pk_mul_f32 v[34:35], v[34:35], v[240:241]
	v_pk_mul_f32 v[36:37], v[36:37], v[242:243]
	global_store_dwordx4 v162, v[34:37], s[58:59] offset:128
	v_pk_mul_f32 v[38:39], v[38:39], v[142:143] op_sel_hi:[1,0]
	v_pk_mul_f32 v[40:41], v[40:41], v[142:143] op_sel_hi:[1,0]
	v_pk_mul_f32 v[38:39], v[38:39], v[244:245]
	v_pk_mul_f32 v[40:41], v[40:41], v[246:247]
	global_store_dwordx4 v162, v[38:41], s[58:59] offset:160
	v_pk_mul_f32 v[42:43], v[42:43], v[142:143] op_sel_hi:[1,0]
	v_pk_mul_f32 v[44:45], v[44:45], v[142:143] op_sel_hi:[1,0]
	v_pk_mul_f32 v[42:43], v[42:43], v[248:249]
	v_pk_mul_f32 v[44:45], v[44:45], v[250:251]
	global_store_dwordx4 v162, v[42:45], s[58:59] offset:192
	v_pk_mul_f32 v[46:47], v[46:47], v[142:143] op_sel_hi:[1,0]
	v_pk_mul_f32 v[48:49], v[48:49], v[142:143] op_sel_hi:[1,0]
	v_pk_mul_f32 v[46:47], v[46:47], v[252:253]
	v_pk_mul_f32 v[48:49], v[48:49], v[254:255]
	global_store_dwordx4 v162, v[46:49], s[58:59] offset:224
	v_pk_mul_f32 v[18:19], v[18:19], v[144:145] op_sel_hi:[1,0]
	v_pk_mul_f32 v[20:21], v[20:21], v[144:145] op_sel_hi:[1,0]
	v_pk_mul_f32 v[18:19], v[18:19], v[224:225]
	v_pk_mul_f32 v[20:21], v[20:21], v[226:227]
	global_store_dwordx4 v162, v[18:21], s[60:61]
	v_pk_mul_f32 v[22:23], v[22:23], v[144:145] op_sel_hi:[1,0]
	v_pk_mul_f32 v[24:25], v[24:25], v[144:145] op_sel_hi:[1,0]
	v_pk_mul_f32 v[22:23], v[22:23], v[228:229]
	v_pk_mul_f32 v[24:25], v[24:25], v[230:231]
	global_store_dwordx4 v162, v[22:25], s[60:61] offset:32
	v_pk_mul_f32 v[26:27], v[26:27], v[144:145] op_sel_hi:[1,0]
	v_pk_mul_f32 v[28:29], v[28:29], v[144:145] op_sel_hi:[1,0]
	v_pk_mul_f32 v[26:27], v[26:27], v[232:233]
	v_pk_mul_f32 v[28:29], v[28:29], v[234:235]
	global_store_dwordx4 v162, v[26:29], s[60:61] offset:64
	v_pk_mul_f32 v[30:31], v[30:31], v[144:145] op_sel_hi:[1,0]
	v_pk_mul_f32 v[32:33], v[32:33], v[144:145] op_sel_hi:[1,0]
	v_pk_mul_f32 v[30:31], v[30:31], v[236:237]
	v_pk_mul_f32 v[32:33], v[32:33], v[238:239]
	global_store_dwordx4 v162, v[30:33], s[60:61] offset:96
	v_pk_mul_f32 v[2:3], v[2:3], v[144:145] op_sel_hi:[1,0]
	v_pk_mul_f32 v[4:5], v[4:5], v[144:145] op_sel_hi:[1,0]
	v_pk_mul_f32 v[2:3], v[2:3], v[240:241]
	v_pk_mul_f32 v[4:5], v[4:5], v[242:243]
	global_store_dwordx4 v162, v[2:5], s[60:61] offset:128
	v_pk_mul_f32 v[6:7], v[6:7], v[144:145] op_sel_hi:[1,0]
	v_pk_mul_f32 v[8:9], v[8:9], v[144:145] op_sel_hi:[1,0]
	v_pk_mul_f32 v[6:7], v[6:7], v[244:245]
	v_pk_mul_f32 v[8:9], v[8:9], v[246:247]
	global_store_dwordx4 v162, v[6:9], s[60:61] offset:160
	v_pk_mul_f32 v[10:11], v[10:11], v[144:145] op_sel_hi:[1,0]
	v_pk_mul_f32 v[12:13], v[12:13], v[144:145] op_sel_hi:[1,0]
	v_pk_mul_f32 v[10:11], v[10:11], v[248:249]
	v_pk_mul_f32 v[12:13], v[12:13], v[250:251]
	global_store_dwordx4 v162, v[10:13], s[60:61] offset:192
	v_pk_mul_f32 v[14:15], v[14:15], v[144:145] op_sel_hi:[1,0]
	v_pk_mul_f32 v[16:17], v[16:17], v[144:145] op_sel_hi:[1,0]
	v_pk_mul_f32 v[14:15], v[14:15], v[252:253]
	v_pk_mul_f32 v[16:17], v[16:17], v[254:255]
	global_store_dwordx4 v162, v[14:17], s[60:61] offset:224
	s_add_i32 s3, s3, s33
	s_cmp_lt_i32 s3, 64
	s_cbranch_scc1 .LBB0_554
	s_branch .LBB0_639
; __device__ void phase_gemm2(const Params& p, char* lds, int bid, int nb, bool fused) {
;     ...
;       for (int tt = 0; tt < 4; ++tt) {
;         const int tok = m0 + wr * 128 + tt * 32 + l31;
;         const float* xr = p.x + (size_t)tok * DM + n0 + wc * 64;
;         float ss = 0.f;
; #pragma unroll
;         for (int ct = 0; ct < 2; ++ct)
; #pragma unroll
;           for (int rq = 0; rq < 4; ++rq) {
;             const f32x4 xv = *(const f32x4*)(xr + ct * 32 + 8 * rq + 4 * h);
; #pragma unroll
;             for (int e = 0; e < 4; ++e) { acc[ct][tt][rq * 4 + e] += xv[e]; ss += acc[ct][tt][rq * 4 + e] * acc[ct][tt][rq * 4 + e]; }
;           }
;         ss += __shfl_xor(ss, 32);
;         olds[tt] = 0.f;
;         if (h == 0) olds[tt] = atomicAdd(p.ssq + tok, ss);
.Lp5_slow:
	v_or_b32_e32 v130, s38, v146
	v_add_u32_e32 v152, s5, v130
	v_ashrrev_i32_e32 v153, 31, v152
	v_lshlrev_b64 v[154:155], 12, v[152:153]
	s_ashr_i32 s35, s34, 31
	v_lshl_add_u64 v[130:131], s[24:25], 0, v[154:155]
	v_lshl_add_u64 v[130:131], s[34:35], 2, v[130:131]
	s_lshl_b32 s14, s4, 2
	v_lshl_add_u64 v[130:131], v[130:131], 0, s[14:15]
	v_lshl_add_u64 v[142:143], v[130:131], 0, v[150:151]
	s_barrier
	global_load_dwordx4 v[130:133], v[142:143], off
	global_load_dwordx4 v[134:137], v[142:143], off offset:32
	global_load_dwordx4 v[138:141], v[142:143], off offset:64
	global_load_dwordx4 v[162:165], v[142:143], off offset:96
	global_load_dwordx4 v[166:169], v[142:143], off offset:128
	global_load_dwordx4 v[170:173], v[142:143], off offset:160
	global_load_dwordx4 v[174:177], v[142:143], off offset:192
	global_load_dwordx4 v[178:181], v[142:143], off offset:224
	v_cmp_lt_i32_e32 vcc, v156, v157
	s_waitcnt vmcnt(7)
	v_pk_add_f32 v[146:147], v[98:99], v[130:131]
	v_pk_add_f32 v[148:149], v[100:101], v[132:133]
	v_pk_mul_f32 v[98:99], v[146:147], v[146:147]
	v_cndmask_b32_e32 v142, v1, v156, vcc
	v_pk_mul_f32 v[100:101], v[148:149], v[148:149]
	v_add_f32_e32 v98, v98, v99
	v_lshlrev_b32_e32 v160, 2, v142
	s_waitcnt vmcnt(6)
	v_pk_add_f32 v[142:143], v[102:103], v[134:135]
	v_add_f32_e32 v98, v100, v98
	s_waitcnt vmcnt(4)
	v_pk_add_f32 v[134:135], v[110:111], v[162:163]
	v_pk_mul_f32 v[110:111], v[142:143], v[142:143]
	v_add_f32_e32 v98, v101, v98
	v_pk_add_f32 v[144:145], v[104:105], v[136:137]
	v_add_f32_e32 v98, v110, v98
	v_pk_add_f32 v[136:137], v[112:113], v[164:165]
	v_pk_mul_f32 v[112:113], v[144:145], v[144:145]
	v_add_f32_e32 v98, v111, v98
	v_pk_add_f32 v[138:139], v[106:107], v[138:139]
	v_add_f32_e32 v98, v112, v98
	s_waitcnt vmcnt(3)
	v_pk_add_f32 v[130:131], v[114:115], v[166:167]
	s_waitcnt vmcnt(2)
	v_pk_add_f32 v[114:115], v[118:119], v[170:171]
	v_pk_mul_f32 v[118:119], v[138:139], v[138:139]
	v_add_f32_e32 v98, v113, v98
	v_pk_add_f32 v[140:141], v[108:109], v[140:141]
	v_add_f32_e32 v98, v118, v98
	v_pk_add_f32 v[132:133], v[116:117], v[168:169]
	v_pk_add_f32 v[116:117], v[120:121], v[172:173]
	v_pk_mul_f32 v[120:121], v[140:141], v[140:141]
	v_add_f32_e32 v98, v119, v98
	v_add_f32_e32 v98, v120, v98
	s_waitcnt vmcnt(1)
	v_pk_add_f32 v[106:107], v[122:123], v[174:175]
	v_pk_mul_f32 v[122:123], v[134:135], v[134:135]
	v_add_f32_e32 v98, v121, v98
	v_add_f32_e32 v98, v122, v98
	v_pk_add_f32 v[108:109], v[124:125], v[176:177]
	v_pk_mul_f32 v[124:125], v[136:137], v[136:137]
	v_add_f32_e32 v98, v123, v98
	v_add_f32_e32 v98, v124, v98
	s_waitcnt vmcnt(0)
	v_pk_add_f32 v[102:103], v[126:127], v[178:179]
	v_pk_mul_f32 v[126:127], v[130:131], v[130:131]
	v_add_f32_e32 v98, v125, v98
	v_add_f32_e32 v98, v126, v98
	v_pk_add_f32 v[104:105], v[128:129], v[180:181]
	v_pk_mul_f32 v[128:129], v[132:133], v[132:133]
	v_add_f32_e32 v98, v127, v98
	v_add_f32_e32 v98, v128, v98
	v_pk_mul_f32 v[162:163], v[114:115], v[114:115]
	v_add_f32_e32 v98, v129, v98
	v_add_f32_e32 v98, v162, v98
	v_pk_mul_f32 v[164:165], v[116:117], v[116:117]
	v_add_f32_e32 v98, v163, v98
	v_add_f32_e32 v98, v164, v98
	v_pk_mul_f32 v[166:167], v[106:107], v[106:107]
	v_add_f32_e32 v98, v165, v98
	v_add_f32_e32 v98, v166, v98
	v_pk_mul_f32 v[168:169], v[108:109], v[108:109]
	v_add_f32_e32 v98, v167, v98
	v_add_f32_e32 v98, v168, v98
	v_pk_mul_f32 v[170:171], v[102:103], v[102:103]
	v_add_f32_e32 v98, v169, v98
	v_add_f32_e32 v98, v170, v98
	v_pk_mul_f32 v[172:173], v[104:105], v[104:105]
	v_add_f32_e32 v98, v171, v98
	v_add_f32_e32 v98, v172, v98
	v_add_f32_e32 v98, v173, v98
	ds_bpermute_b32 v99, v160, v98
	v_cmp_eq_u32_e32 vcc, 0, v159
	v_mov_b32_e32 v128, 0
	s_and_saveexec_b64 s[4:5], vcc
	s_cbranch_execz .LBB0_556
	s_waitcnt lgkmcnt(0)
	v_add_f32_e32 v100, v98, v99
	v_lshl_add_u64 v[98:99], v[152:153], 2, s[18:19]
	global_atomic_add_f32 v128, v[98:99], v100, off sc0
